# speedup vs baseline: 1.0461x; 1.0042x over previous
.LBB0_90:
	v_mov_b32_e32 v134, v204
	s_waitcnt vmcnt(0)
	v_and_b32_e32 v0, 15, v134
	v_ashrrev_i32_e32 v135, 2, v134
	v_and_b32_e32 v136, 0xffffffc0, v135
	v_or_b32_e32 v135, s10, v0
	v_add_u32_e32 v138, v135, v136
	v_ashrrev_i32_e32 v139, 31, v138
	v_lshl_add_u64 v[138:139], v[138:139], 3, v[130:131]
	s_barrier
	flat_load_dwordx2 v[138:139], v[138:139]
	v_mov_b32_e32 v140, 0x358637bd
	s_mov_b64 s[0:1], 0x1e364800
	v_mov_b32_e32 v253, 0x358637bd
	s_waitcnt vmcnt(0) lgkmcnt(0)
	v_ffbh_u32_e32 v137, v139
	v_min_u32_e32 v137, 32, v137
	v_lshlrev_b64 v[138:139], v137, v[138:139]
	v_min_u32_e32 v138, 1, v138
	v_or_b32_e32 v138, v139, v138
	v_cvt_f32_u32_e32 v138, v138
	v_sub_u32_e32 v137, 32, v137
	v_ldexp_f32 v137, v138, v137
	v_fmamk_f32 v137, v137, 0x30000000, v140
	v_cmp_gt_f32_e32 vcc, s33, v137
	v_mul_f32_e32 v138, 0x4b800000, v137
	s_nop 0
	v_cndmask_b32_e32 v137, v137, v138, vcc
	v_rsq_f32_e32 v137, v137
	s_nop 0
	v_mul_f32_e32 v138, 0x45800000, v137
	v_cndmask_b32_e32 v137, v137, v138, vcc
	v_mul_f32_e32 v137, 0x3e0293ee, v137
	v_mul_f32_e32 v126, v126, v137
	v_mul_f32_e32 v127, v127, v137
	v_or_b32_e32 v138, v136, v0
	v_mul_f32_e32 v139, v128, v137
	v_cvt_pk_bf16_f32 v128, v126, v127
	v_lshrrev_b32_e32 v126, 1, v134
	v_mul_lo_u32 v138, v138, s72
	v_mul_f32_e32 v129, v129, v137
	v_and_b32_e32 v126, 24, v126
	v_and_b32_e32 v127, 0xc0, v134
	v_mul_f32_e32 v114, v114, v137
	v_mul_f32_e32 v115, v115, v137
	v_mul_f32_e32 v116, v116, v137
	v_mul_f32_e32 v117, v117, v137
	v_cvt_pk_bf16_f32 v129, v139, v129
	v_add3_u32 v138, v138, v127, v126
	v_cvt_pk_bf16_f32 v114, v114, v115
	v_cvt_pk_bf16_f32 v115, v116, v117
	ds_write2_b64 v138, v[128:129], v[114:115] offset1:4
	v_mul_f32_e32 v114, v122, v137
	v_mul_f32_e32 v115, v123, v137
	v_mul_f32_e32 v116, v124, v137
	v_mul_f32_e32 v117, v125, v137
	v_cvt_pk_bf16_f32 v114, v114, v115
	v_cvt_pk_bf16_f32 v115, v116, v117
	v_mul_f32_e32 v116, v118, v137
	v_mul_f32_e32 v117, v119, v137
	v_mul_f32_e32 v118, v120, v137
	v_mul_f32_e32 v119, v121, v137
	v_cvt_pk_bf16_f32 v116, v116, v117
	v_cvt_pk_bf16_f32 v117, v118, v119
	ds_write2_b64 v138, v[114:115], v[116:117] offset0:32 offset1:36
	v_or_b32_e32 v116, 16, v136
	v_add_u32_e32 v114, v116, v135
	v_ashrrev_i32_e32 v115, 31, v114
	v_lshl_add_u64 v[114:115], v[114:115], 3, v[130:131]
	flat_load_dwordx2 v[114:115], v[114:115]
	s_waitcnt vmcnt(0) lgkmcnt(0)
	v_ffbh_u32_e32 v117, v115
	v_min_u32_e32 v117, 32, v117
	v_lshlrev_b64 v[114:115], v117, v[114:115]
	v_min_u32_e32 v114, 1, v114
	v_or_b32_e32 v114, v115, v114
	v_cvt_f32_u32_e32 v114, v114
	v_sub_u32_e32 v115, 32, v117
	v_ldexp_f32 v114, v114, v115
	v_fmamk_f32 v114, v114, 0x30000000, v140
	v_cmp_gt_f32_e32 vcc, s33, v114
	v_mul_f32_e32 v115, 0x4b800000, v114
	s_nop 0
	v_cndmask_b32_e32 v114, v114, v115, vcc
	v_rsq_f32_e32 v114, v114
	s_nop 0
	v_mul_f32_e32 v115, 0x45800000, v114
	v_cndmask_b32_e32 v114, v114, v115, vcc
	v_mul_f32_e32 v114, 0x3e0293ee, v114
	v_or_b32_e32 v115, v116, v0
	v_mul_lo_u32 v115, v115, s72
	v_mul_f32_e32 v102, v102, v114
	v_mul_f32_e32 v103, v103, v114
	v_mul_f32_e32 v104, v104, v114
	v_mul_f32_e32 v105, v105, v114
	v_mul_f32_e32 v98, v98, v114
	v_mul_f32_e32 v99, v99, v114
	v_mul_f32_e32 v100, v100, v114
	v_mul_f32_e32 v101, v101, v114
	v_cvt_pk_bf16_f32 v102, v102, v103
	v_cvt_pk_bf16_f32 v103, v104, v105
	v_add3_u32 v104, v115, v127, v126
	v_cvt_pk_bf16_f32 v98, v98, v99
	v_cvt_pk_bf16_f32 v99, v100, v101
	ds_write2_b64 v104, v[102:103], v[98:99] offset1:4
	v_mul_f32_e32 v98, v110, v114
	v_mul_f32_e32 v99, v111, v114
	v_mul_f32_e32 v100, v112, v114
	v_mul_f32_e32 v101, v113, v114
	v_cvt_pk_bf16_f32 v98, v98, v99
	v_cvt_pk_bf16_f32 v99, v100, v101
	v_mul_f32_e32 v100, v106, v114
	v_mul_f32_e32 v101, v107, v114
	v_mul_f32_e32 v102, v108, v114
	v_mul_f32_e32 v103, v109, v114
	v_cvt_pk_bf16_f32 v100, v100, v101
	v_cvt_pk_bf16_f32 v101, v102, v103
	ds_write2_b64 v104, v[98:99], v[100:101] offset0:32 offset1:36
	v_or_b32_e32 v100, 32, v136
	v_add_u32_e32 v98, v100, v135
	v_ashrrev_i32_e32 v99, 31, v98
	v_lshl_add_u64 v[98:99], v[98:99], 3, v[130:131]
	flat_load_dwordx2 v[98:99], v[98:99]
	s_waitcnt vmcnt(0) lgkmcnt(0)
	v_ffbh_u32_e32 v101, v99
	v_min_u32_e32 v101, 32, v101
	v_lshlrev_b64 v[98:99], v101, v[98:99]
	v_min_u32_e32 v98, 1, v98
	v_or_b32_e32 v98, v99, v98
	v_cvt_f32_u32_e32 v98, v98
	v_sub_u32_e32 v99, 32, v101
	v_ldexp_f32 v98, v98, v99
	v_fmamk_f32 v98, v98, 0x30000000, v140
	v_cmp_gt_f32_e32 vcc, s33, v98
	v_mul_f32_e32 v99, 0x4b800000, v98
	s_nop 0
	v_cndmask_b32_e32 v98, v98, v99, vcc
	v_rsq_f32_e32 v98, v98
	s_nop 0
	v_mul_f32_e32 v99, 0x45800000, v98
	v_cndmask_b32_e32 v98, v98, v99, vcc
	v_mul_f32_e32 v98, 0x3e0293ee, v98
	v_or_b32_e32 v99, v100, v0
	v_mul_lo_u32 v99, v99, s72
	v_mul_f32_e32 v86, v86, v98
	v_mul_f32_e32 v87, v87, v98
	v_mul_f32_e32 v88, v88, v98
	v_mul_f32_e32 v89, v89, v98
	v_mul_f32_e32 v82, v82, v98
	v_mul_f32_e32 v83, v83, v98
	v_mul_f32_e32 v84, v84, v98
	v_mul_f32_e32 v85, v85, v98
	v_cvt_pk_bf16_f32 v86, v86, v87
	v_cvt_pk_bf16_f32 v87, v88, v89
	v_add3_u32 v88, v99, v127, v126
	v_cvt_pk_bf16_f32 v82, v82, v83
	v_cvt_pk_bf16_f32 v83, v84, v85
	ds_write2_b64 v88, v[86:87], v[82:83] offset1:4
	v_mul_f32_e32 v82, v94, v98
	v_mul_f32_e32 v83, v95, v98
	v_mul_f32_e32 v84, v96, v98
	v_mul_f32_e32 v85, v97, v98
	v_cvt_pk_bf16_f32 v82, v82, v83
	v_cvt_pk_bf16_f32 v83, v84, v85
	v_mul_f32_e32 v84, v90, v98
	v_mul_f32_e32 v85, v91, v98
	v_mul_f32_e32 v86, v92, v98
	v_mul_f32_e32 v87, v93, v98
	v_cvt_pk_bf16_f32 v84, v84, v85
	v_cvt_pk_bf16_f32 v85, v86, v87
	ds_write2_b64 v88, v[82:83], v[84:85] offset0:32 offset1:36
	v_or_b32_e32 v84, 48, v136
	v_add_u32_e32 v82, v84, v135
	v_ashrrev_i32_e32 v83, 31, v82
	v_lshl_add_u64 v[82:83], v[82:83], 3, v[130:131]
	flat_load_dwordx2 v[82:83], v[82:83]
	s_waitcnt vmcnt(0) lgkmcnt(0)
	v_ffbh_u32_e32 v85, v83
	v_min_u32_e32 v85, 32, v85
	v_lshlrev_b64 v[82:83], v85, v[82:83]
	v_min_u32_e32 v82, 1, v82
	v_or_b32_e32 v82, v83, v82
	v_cvt_f32_u32_e32 v82, v82
	v_sub_u32_e32 v83, 32, v85
	v_ldexp_f32 v82, v82, v83
	v_fmamk_f32 v82, v82, 0x30000000, v140
	v_cmp_gt_f32_e32 vcc, s33, v82
	v_mul_f32_e32 v83, 0x4b800000, v82
	s_nop 0
	v_cndmask_b32_e32 v82, v82, v83, vcc
	v_rsq_f32_e32 v82, v82
	s_nop 0
	v_mul_f32_e32 v83, 0x45800000, v82
	v_cndmask_b32_e32 v82, v82, v83, vcc
	v_mul_f32_e32 v82, 0x3e0293ee, v82
	v_or_b32_e32 v83, v84, v0
	v_mul_lo_u32 v83, v83, s72
	v_mul_f32_e32 v70, v70, v82
	v_mul_f32_e32 v71, v71, v82
	v_mul_f32_e32 v72, v72, v82
	v_mul_f32_e32 v73, v73, v82
	v_mul_f32_e32 v66, v66, v82
	v_mul_f32_e32 v67, v67, v82
	v_mul_f32_e32 v68, v68, v82
	v_mul_f32_e32 v69, v69, v82
	v_cvt_pk_bf16_f32 v70, v70, v71
	v_cvt_pk_bf16_f32 v71, v72, v73
	v_add3_u32 v72, v83, v127, v126
	v_cvt_pk_bf16_f32 v66, v66, v67
	v_cvt_pk_bf16_f32 v67, v68, v69
	ds_write2_b64 v72, v[70:71], v[66:67] offset1:4
	v_mul_f32_e32 v66, v78, v82
	v_mul_f32_e32 v67, v79, v82
	v_mul_f32_e32 v68, v80, v82
	v_mul_f32_e32 v69, v81, v82
	v_cvt_pk_bf16_f32 v66, v66, v67
	v_cvt_pk_bf16_f32 v67, v68, v69
	v_mul_f32_e32 v68, v74, v82
	v_mul_f32_e32 v69, v75, v82
	v_mul_f32_e32 v70, v76, v82
	v_mul_f32_e32 v71, v77, v82
	v_cvt_pk_bf16_f32 v68, v68, v69
	v_cvt_pk_bf16_f32 v69, v70, v71
	ds_write2_b64 v72, v[66:67], v[68:69] offset0:32 offset1:36
	v_add_u32_e32 v68, 0x80, v136
	v_add_u32_e32 v66, v68, v135
	v_ashrrev_i32_e32 v67, 31, v66
	v_lshl_add_u64 v[66:67], v[66:67], 3, v[130:131]
	flat_load_dwordx2 v[66:67], v[66:67]
	s_waitcnt vmcnt(0) lgkmcnt(0)
	v_ffbh_u32_e32 v69, v67
	v_min_u32_e32 v69, 32, v69
	v_lshlrev_b64 v[66:67], v69, v[66:67]
	v_min_u32_e32 v66, 1, v66
	v_or_b32_e32 v66, v67, v66
	v_cvt_f32_u32_e32 v66, v66
	v_sub_u32_e32 v67, 32, v69
	v_ldexp_f32 v66, v66, v67
	v_fmamk_f32 v66, v66, 0x30000000, v140
	v_cmp_gt_f32_e32 vcc, s33, v66
	v_mul_f32_e32 v67, 0x4b800000, v66
	s_nop 0
	v_cndmask_b32_e32 v66, v66, v67, vcc
	v_rsq_f32_e32 v66, v66
	s_nop 0
	v_mul_f32_e32 v67, 0x45800000, v66
	v_cndmask_b32_e32 v66, v66, v67, vcc
	v_mul_f32_e32 v66, 0x3e0293ee, v66
	v_or_b32_e32 v67, v68, v0
	v_mul_lo_u32 v67, v67, s72
	v_mul_f32_e32 v54, v54, v66
	v_mul_f32_e32 v55, v55, v66
	v_mul_f32_e32 v56, v56, v66
	v_mul_f32_e32 v57, v57, v66
	v_mul_f32_e32 v50, v50, v66
	v_mul_f32_e32 v51, v51, v66
	v_mul_f32_e32 v52, v52, v66
	v_mul_f32_e32 v53, v53, v66
	v_cvt_pk_bf16_f32 v54, v54, v55
	v_cvt_pk_bf16_f32 v55, v56, v57
	v_add3_u32 v56, v67, v127, v126
	v_cvt_pk_bf16_f32 v50, v50, v51
	v_cvt_pk_bf16_f32 v51, v52, v53
	ds_write2_b64 v56, v[54:55], v[50:51] offset1:4
	v_mul_f32_e32 v50, v62, v66
	v_mul_f32_e32 v51, v63, v66
	v_mul_f32_e32 v52, v64, v66
	v_mul_f32_e32 v53, v65, v66
	v_cvt_pk_bf16_f32 v50, v50, v51
	v_cvt_pk_bf16_f32 v51, v52, v53
	v_mul_f32_e32 v52, v58, v66
	v_mul_f32_e32 v53, v59, v66
	v_mul_f32_e32 v54, v60, v66
	v_mul_f32_e32 v55, v61, v66
	v_cvt_pk_bf16_f32 v52, v52, v53
	v_cvt_pk_bf16_f32 v53, v54, v55
	ds_write2_b64 v56, v[50:51], v[52:53] offset0:32 offset1:36
	v_add_u32_e32 v52, 0x90, v136
	v_add_u32_e32 v50, v52, v135
	v_ashrrev_i32_e32 v51, 31, v50
	v_lshl_add_u64 v[50:51], v[50:51], 3, v[130:131]
	flat_load_dwordx2 v[50:51], v[50:51]
	s_waitcnt vmcnt(0) lgkmcnt(0)
	v_ffbh_u32_e32 v53, v51
	v_min_u32_e32 v53, 32, v53
	v_lshlrev_b64 v[50:51], v53, v[50:51]
	v_min_u32_e32 v50, 1, v50
	v_or_b32_e32 v50, v51, v50
	v_cvt_f32_u32_e32 v50, v50
	v_sub_u32_e32 v51, 32, v53
	v_ldexp_f32 v50, v50, v51
	v_fmamk_f32 v50, v50, 0x30000000, v140
	v_cmp_gt_f32_e32 vcc, s33, v50
	v_mul_f32_e32 v51, 0x4b800000, v50
	s_nop 0
	v_cndmask_b32_e32 v50, v50, v51, vcc
	v_rsq_f32_e32 v50, v50
	s_nop 0
	v_mul_f32_e32 v51, 0x45800000, v50
	v_cndmask_b32_e32 v50, v50, v51, vcc
	v_mul_f32_e32 v50, 0x3e0293ee, v50
	v_or_b32_e32 v51, v52, v0
	v_mul_lo_u32 v51, v51, s72
	v_mul_f32_e32 v38, v38, v50
	v_mul_f32_e32 v39, v39, v50
	v_mul_f32_e32 v40, v40, v50
	v_mul_f32_e32 v41, v41, v50
	v_mul_f32_e32 v34, v34, v50
	v_mul_f32_e32 v35, v35, v50
	v_mul_f32_e32 v36, v36, v50
	v_mul_f32_e32 v37, v37, v50
	v_cvt_pk_bf16_f32 v38, v38, v39
	v_cvt_pk_bf16_f32 v39, v40, v41
	v_add3_u32 v40, v51, v127, v126
	v_cvt_pk_bf16_f32 v34, v34, v35
	v_cvt_pk_bf16_f32 v35, v36, v37
	ds_write2_b64 v40, v[38:39], v[34:35] offset1:4
	v_mul_f32_e32 v34, v46, v50
	v_mul_f32_e32 v35, v47, v50
	v_mul_f32_e32 v36, v48, v50
	v_mul_f32_e32 v37, v49, v50
	v_cvt_pk_bf16_f32 v34, v34, v35
	v_cvt_pk_bf16_f32 v35, v36, v37
	v_mul_f32_e32 v36, v42, v50
	v_mul_f32_e32 v37, v43, v50
	v_mul_f32_e32 v38, v44, v50
	v_mul_f32_e32 v39, v45, v50
	v_cvt_pk_bf16_f32 v36, v36, v37
	v_cvt_pk_bf16_f32 v37, v38, v39
	ds_write2_b64 v40, v[34:35], v[36:37] offset0:32 offset1:36
	v_add_u32_e32 v36, 0xa0, v136
	v_add_u32_e32 v34, v36, v135
	v_ashrrev_i32_e32 v35, 31, v34
	v_lshl_add_u64 v[34:35], v[34:35], 3, v[130:131]
	flat_load_dwordx2 v[34:35], v[34:35]
	s_waitcnt vmcnt(0) lgkmcnt(0)
	v_ffbh_u32_e32 v37, v35
	v_min_u32_e32 v37, 32, v37
	v_lshlrev_b64 v[34:35], v37, v[34:35]
	v_min_u32_e32 v34, 1, v34
	v_or_b32_e32 v34, v35, v34
	v_cvt_f32_u32_e32 v34, v34
	v_sub_u32_e32 v35, 32, v37
	v_ldexp_f32 v34, v34, v35
	v_fmamk_f32 v34, v34, 0x30000000, v140
	v_cmp_gt_f32_e32 vcc, s33, v34
	v_mul_f32_e32 v35, 0x4b800000, v34
	s_nop 0
	v_cndmask_b32_e32 v34, v34, v35, vcc
	v_rsq_f32_e32 v34, v34
	s_nop 0
	v_mul_f32_e32 v35, 0x45800000, v34
	v_cndmask_b32_e32 v34, v34, v35, vcc
	v_mul_f32_e32 v34, 0x3e0293ee, v34
	v_or_b32_e32 v35, v36, v0
	v_mul_lo_u32 v35, v35, s72
	v_mul_f32_e32 v22, v22, v34
	v_mul_f32_e32 v23, v23, v34
	v_mul_f32_e32 v24, v24, v34
	v_mul_f32_e32 v25, v25, v34
	v_mul_f32_e32 v18, v18, v34
	v_mul_f32_e32 v19, v19, v34
	v_mul_f32_e32 v20, v20, v34
	v_mul_f32_e32 v21, v21, v34
	v_cvt_pk_bf16_f32 v22, v22, v23
	v_cvt_pk_bf16_f32 v23, v24, v25
	v_add3_u32 v24, v35, v127, v126
	v_cvt_pk_bf16_f32 v18, v18, v19
	v_cvt_pk_bf16_f32 v19, v20, v21
	ds_write2_b64 v24, v[22:23], v[18:19] offset1:4
	v_mul_f32_e32 v18, v30, v34
	v_mul_f32_e32 v19, v31, v34
	v_mul_f32_e32 v20, v32, v34
	v_mul_f32_e32 v21, v33, v34
	v_cvt_pk_bf16_f32 v18, v18, v19
	v_cvt_pk_bf16_f32 v19, v20, v21
	v_mul_f32_e32 v20, v26, v34
	v_mul_f32_e32 v21, v27, v34
	v_mul_f32_e32 v22, v28, v34
	v_mul_f32_e32 v23, v29, v34
	v_cvt_pk_bf16_f32 v20, v20, v21
	v_cvt_pk_bf16_f32 v21, v22, v23
	ds_write2_b64 v24, v[18:19], v[20:21] offset0:32 offset1:36
	v_add_u32_e32 v20, 0xb0, v136
	v_add_u32_e32 v18, v20, v135
	v_ashrrev_i32_e32 v19, 31, v18
	v_lshl_add_u64 v[18:19], v[18:19], 3, v[130:131]
	flat_load_dwordx2 v[18:19], v[18:19]
	v_or_b32_e32 v0, v20, v0
	v_mul_lo_u32 v0, v0, s72
	v_add3_u32 v0, v0, v127, v126
	s_waitcnt vmcnt(0) lgkmcnt(0)
	v_ffbh_u32_e32 v21, v19
	v_min_u32_e32 v21, 32, v21
	v_lshlrev_b64 v[18:19], v21, v[18:19]
	v_min_u32_e32 v18, 1, v18
	v_or_b32_e32 v18, v19, v18
	v_cvt_f32_u32_e32 v18, v18
	v_sub_u32_e32 v19, 32, v21
	v_ldexp_f32 v18, v18, v19
	v_fmamk_f32 v18, v18, 0x30000000, v140
	v_cmp_gt_f32_e32 vcc, s33, v18
	v_mul_f32_e32 v19, 0x4b800000, v18
	s_nop 0
	v_cndmask_b32_e32 v18, v18, v19, vcc
	v_rsq_f32_e32 v18, v18
	s_nop 0
	v_mul_f32_e32 v19, 0x45800000, v18
	v_cndmask_b32_e32 v18, v18, v19, vcc
	v_mul_f32_e32 v18, 0x3e0293ee, v18
	v_mul_f32_e32 v6, v6, v18
	v_mul_f32_e32 v7, v7, v18
	v_mul_f32_e32 v8, v8, v18
	v_mul_f32_e32 v9, v9, v18
	v_mul_f32_e32 v2, v2, v18
	v_mul_f32_e32 v3, v3, v18
	v_mul_f32_e32 v4, v4, v18
	v_mul_f32_e32 v5, v5, v18
	v_cvt_pk_bf16_f32 v6, v6, v7
	v_cvt_pk_bf16_f32 v7, v8, v9
	v_cvt_pk_bf16_f32 v2, v2, v3
	v_cvt_pk_bf16_f32 v3, v4, v5
	ds_write2_b64 v0, v[6:7], v[2:3] offset1:4
	v_mul_f32_e32 v2, v14, v18
	v_mul_f32_e32 v3, v15, v18
	v_mul_f32_e32 v4, v16, v18
	v_mul_f32_e32 v5, v17, v18
	v_cvt_pk_bf16_f32 v2, v2, v3
	v_cvt_pk_bf16_f32 v3, v4, v5
	v_mul_f32_e32 v4, v10, v18
	v_mul_f32_e32 v5, v11, v18
	v_mul_f32_e32 v6, v12, v18
	v_mul_f32_e32 v7, v13, v18
	v_cvt_pk_bf16_f32 v4, v4, v5
	v_cvt_pk_bf16_f32 v5, v6, v7
	ds_write2_b64 v0, v[2:3], v[4:5] offset0:32 offset1:36
	v_lshlrev_b32_e32 v0, 4, v134
	v_lshl_add_u64 v[2:3], s[8:9], 1, v[132:133]
	v_and_b32_e32 v0, 0x1f0, v0
	v_lshl_add_u64 v[2:3], v[2:3], 0, v[0:1]
	v_ashrrev_i32_e32 v8, 5, v134
	v_lshl_add_u64 v[2:3], v[2:3], 0, s[0:1]
	v_mad_u64_u32 v[4:5], s[0:1], v8, s72, v[0:1]
	s_waitcnt lgkmcnt(0)
	s_barrier
	ds_read_b128 v[4:7], v4
	v_ashrrev_i32_e32 v9, 31, v8
	v_lshlrev_b64 v[8:9], 12, v[8:9]
	v_lshl_add_u64 v[8:9], v[2:3], 0, v[8:9]
	s_waitcnt lgkmcnt(0)
	flat_store_dwordx4 v[8:9], v[4:7] nt
	s_nop 1
	v_add_u32_e32 v4, 0x200, v134
	v_ashrrev_i32_e32 v8, 5, v4
	v_mad_u64_u32 v[4:5], s[0:1], v8, s72, v[0:1]
	ds_read_b128 v[4:7], v4
	v_ashrrev_i32_e32 v9, 31, v8
	v_lshlrev_b64 v[8:9], 12, v[8:9]
	v_lshl_add_u64 v[8:9], v[2:3], 0, v[8:9]
	s_waitcnt lgkmcnt(0)
	flat_store_dwordx4 v[8:9], v[4:7] nt
	s_nop 1
	v_add_u32_e32 v4, 0x400, v134
	v_ashrrev_i32_e32 v8, 5, v4
	v_mad_u64_u32 v[4:5], s[0:1], v8, s72, v[0:1]
	ds_read_b128 v[4:7], v4
	v_ashrrev_i32_e32 v9, 31, v8
	v_lshlrev_b64 v[8:9], 12, v[8:9]
	v_lshl_add_u64 v[8:9], v[2:3], 0, v[8:9]
	s_waitcnt lgkmcnt(0)
	flat_store_dwordx4 v[8:9], v[4:7] nt
	s_nop 1
	v_add_u32_e32 v4, 0x600, v134
	v_ashrrev_i32_e32 v8, 5, v4
	v_mad_u64_u32 v[4:5], s[0:1], v8, s72, v[0:1]
	ds_read_b128 v[4:7], v4
	v_ashrrev_i32_e32 v9, 31, v8
	v_lshlrev_b64 v[8:9], 12, v[8:9]
	v_lshl_add_u64 v[8:9], v[2:3], 0, v[8:9]
	s_waitcnt lgkmcnt(0)
	flat_store_dwordx4 v[8:9], v[4:7] nt
	s_nop 1
	v_add_u32_e32 v4, 0x800, v134
	v_ashrrev_i32_e32 v8, 5, v4
	v_mad_u64_u32 v[4:5], s[0:1], v8, s72, v[0:1]
	ds_read_b128 v[4:7], v4
	v_ashrrev_i32_e32 v9, 31, v8
	v_lshlrev_b64 v[8:9], 12, v[8:9]
	v_lshl_add_u64 v[8:9], v[2:3], 0, v[8:9]
	s_waitcnt lgkmcnt(0)
	flat_store_dwordx4 v[8:9], v[4:7] nt
	s_nop 1
	v_add_u32_e32 v4, 0xa00, v134
	v_ashrrev_i32_e32 v8, 5, v4
	v_mad_u64_u32 v[4:5], s[0:1], v8, s72, v[0:1]
	ds_read_b128 v[4:7], v4
	v_ashrrev_i32_e32 v9, 31, v8
	v_lshlrev_b64 v[8:9], 12, v[8:9]
	v_lshl_add_u64 v[8:9], v[2:3], 0, v[8:9]
	s_waitcnt lgkmcnt(0)
	flat_store_dwordx4 v[8:9], v[4:7] nt
	s_nop 1
	v_add_u32_e32 v4, 0xc00, v134
	v_ashrrev_i32_e32 v8, 5, v4
	v_mad_u64_u32 v[4:5], s[0:1], v8, s72, v[0:1]
	ds_read_b128 v[4:7], v4
	v_ashrrev_i32_e32 v9, 31, v8
	v_lshlrev_b64 v[8:9], 12, v[8:9]
	v_lshl_add_u64 v[8:9], v[2:3], 0, v[8:9]
	s_waitcnt lgkmcnt(0)
	flat_store_dwordx4 v[8:9], v[4:7] nt
	s_nop 1
	v_add_u32_e32 v4, 0xe00, v134
	v_ashrrev_i32_e32 v8, 5, v4
	v_mad_u64_u32 v[4:5], s[0:1], v8, s72, v[0:1]
	ds_read_b128 v[4:7], v4
	v_ashrrev_i32_e32 v9, 31, v8
	v_lshlrev_b64 v[8:9], 12, v[8:9]
	v_lshl_add_u64 v[8:9], v[2:3], 0, v[8:9]
	s_waitcnt lgkmcnt(0)
	flat_store_dwordx4 v[8:9], v[4:7] nt
	s_nop 1
	v_add_u32_e32 v4, 0x1000, v134
	v_ashrrev_i32_e32 v8, 5, v4
	v_mad_u64_u32 v[4:5], s[0:1], v8, s72, v[0:1]
	ds_read_b128 v[4:7], v4
	v_ashrrev_i32_e32 v9, 31, v8
	v_lshlrev_b64 v[8:9], 12, v[8:9]
	v_lshl_add_u64 v[8:9], v[2:3], 0, v[8:9]
	s_waitcnt lgkmcnt(0)
	flat_store_dwordx4 v[8:9], v[4:7] nt
	s_nop 1
	v_add_u32_e32 v4, 0x1200, v134
	v_ashrrev_i32_e32 v8, 5, v4
	v_mad_u64_u32 v[4:5], s[0:1], v8, s72, v[0:1]
	ds_read_b128 v[4:7], v4
	v_ashrrev_i32_e32 v9, 31, v8
	v_lshlrev_b64 v[8:9], 12, v[8:9]
	v_lshl_add_u64 v[8:9], v[2:3], 0, v[8:9]
	s_waitcnt lgkmcnt(0)
	flat_store_dwordx4 v[8:9], v[4:7] nt
	s_nop 1
	v_add_u32_e32 v4, 0x1400, v134
	v_ashrrev_i32_e32 v8, 5, v4
	v_mad_u64_u32 v[4:5], s[0:1], v8, s72, v[0:1]
	ds_read_b128 v[4:7], v4
	v_ashrrev_i32_e32 v9, 31, v8
	v_lshlrev_b64 v[8:9], 12, v[8:9]
	v_lshl_add_u64 v[8:9], v[2:3], 0, v[8:9]
	s_waitcnt lgkmcnt(0)
	flat_store_dwordx4 v[8:9], v[4:7] nt
	s_nop 1
	v_add_u32_e32 v4, 0x1600, v134
	v_ashrrev_i32_e32 v8, 5, v4
	v_mad_u64_u32 v[4:5], s[0:1], v8, s72, v[0:1]
	ds_read_b128 v[4:7], v4
	v_ashrrev_i32_e32 v9, 31, v8
	v_lshlrev_b64 v[8:9], 12, v[8:9]
	v_lshl_add_u64 v[8:9], v[2:3], 0, v[8:9]
	s_waitcnt lgkmcnt(0)
	flat_store_dwordx4 v[8:9], v[4:7] nt
	s_nop 1
	v_add_u32_e32 v4, 0x1800, v134
	v_ashrrev_i32_e32 v8, 5, v4
	v_mad_u64_u32 v[4:5], s[0:1], v8, s72, v[0:1]
	ds_read_b128 v[4:7], v4
	v_ashrrev_i32_e32 v9, 31, v8
	v_lshlrev_b64 v[8:9], 12, v[8:9]
	v_lshl_add_u64 v[8:9], v[2:3], 0, v[8:9]
	s_waitcnt lgkmcnt(0)
	flat_store_dwordx4 v[8:9], v[4:7] nt
	s_nop 1
	v_add_u32_e32 v4, 0x1a00, v134
	v_ashrrev_i32_e32 v8, 5, v4
	v_mad_u64_u32 v[4:5], s[0:1], v8, s72, v[0:1]
	ds_read_b128 v[4:7], v4
	v_ashrrev_i32_e32 v9, 31, v8
	v_lshlrev_b64 v[8:9], 12, v[8:9]
	v_lshl_add_u64 v[8:9], v[2:3], 0, v[8:9]
	s_waitcnt lgkmcnt(0)
	flat_store_dwordx4 v[8:9], v[4:7] nt
	s_nop 1
	v_add_u32_e32 v4, 0x1c00, v134
	v_ashrrev_i32_e32 v8, 5, v4
	v_mad_u64_u32 v[4:5], s[0:1], v8, s72, v[0:1]
	ds_read_b128 v[4:7], v4
	v_ashrrev_i32_e32 v9, 31, v8
	v_lshlrev_b64 v[8:9], 12, v[8:9]
	v_lshl_add_u64 v[8:9], v[2:3], 0, v[8:9]
	s_waitcnt lgkmcnt(0)
	flat_store_dwordx4 v[8:9], v[4:7] nt
	s_nop 1
	v_add_u32_e32 v4, 0x1e00, v134
	v_ashrrev_i32_e32 v8, 5, v4
	v_mad_u64_u32 v[4:5], s[0:1], v8, s72, v[0:1]
	ds_read_b128 v[4:7], v4
	v_ashrrev_i32_e32 v9, 31, v8
	v_lshlrev_b64 v[8:9], 12, v[8:9]
	v_lshl_add_u64 v[2:3], v[2:3], 0, v[8:9]
	s_waitcnt lgkmcnt(0)
	flat_store_dwordx4 v[2:3], v[4:7] nt
	s_waitcnt lgkmcnt(0)
	s_barrier

.LBB0_104:
	v_mov_b32_e32 v140, v204
	s_and_b32 s0, s10, 0xfffff800
	v_bfe_u32 v136, v140, 4, 2
	v_ashrrev_i32_e32 v137, 2, v140
	v_and_b32_e32 v143, 0xffffffc0, v137
	v_lshl_or_b32 v142, v136, 2, s10
	s_add_i32 s9, s8, s0
	v_and_b32_e32 v0, 15, v140
	v_lshrrev_b32_e32 v137, 1, v140
	s_movk_i32 s0, 0x60
	v_lshlrev_b32_e32 v141, 3, v136
	v_add_u32_e32 v136, v142, v143
	v_and_or_b32 v0, v137, s0, v0
	v_ashrrev_i32_e32 v137, 31, v136
	v_lshl_add_u64 v[144:145], v[136:137], 3, v[130:131]
	s_waitcnt vmcnt(0)
	s_barrier
	flat_load_dwordx4 v[136:139], v[144:145]
	s_mov_b32 s0, 0x358637bd
	s_mov_b32 s2, 0x45800000
	v_lshl_or_b32 v148, v143, 1, v141
	s_addk_i32 s9, 0xf000
	s_waitcnt vmcnt(0) lgkmcnt(0)
	v_ffbh_u32_e32 v146, v139
	v_min_u32_e32 v146, 32, v146
	v_lshlrev_b64 v[138:139], v146, v[138:139]
	v_min_u32_e32 v138, 1, v138
	v_or_b32_e32 v138, v139, v138
	v_cvt_f32_u32_e32 v138, v138
	v_sub_u32_e32 v139, 32, v146
	v_ldexp_f32 v139, v138, v139
	v_ffbh_u32_e32 v138, v137
	v_min_u32_e32 v138, 32, v138
	v_lshlrev_b64 v[136:137], v138, v[136:137]
	v_min_u32_e32 v136, 1, v136
	v_or_b32_e32 v136, v137, v136
	v_cvt_f32_u32_e32 v136, v136
	v_sub_u32_e32 v137, 32, v138
	v_ldexp_f32 v138, v136, v137
	v_mov_b64_e32 v[136:137], s[0:1]
	s_brev_b32 s0, 12
	v_pk_fma_f32 v[138:139], v[138:139], s[0:1], v[136:137] op_sel_hi:[1,0,0]
	s_nop 0
	v_mul_f32_e32 v146, 0x4b800000, v138
	v_cmp_gt_f32_e64 s[4:5], s33, v138
	v_cmp_gt_f32_e32 vcc, s33, v139
	s_nop 0
	v_cndmask_b32_e64 v138, v138, v146, s[4:5]
	v_mul_f32_e32 v146, 0x4b800000, v139
	v_cndmask_b32_e32 v139, v139, v146, vcc
	v_rsq_f32_e32 v138, v138
	v_rsq_f32_e32 v139, v139
	s_nop 0
	v_pk_mul_f32 v[146:147], v[138:139], s[2:3] op_sel_hi:[1,0]
	s_nop 0
	v_cndmask_b32_e32 v139, v139, v147, vcc
	v_cndmask_b32_e64 v138, v138, v146, s[4:5]
	flat_load_dwordx4 v[144:147], v[144:145] offset:16
	v_pk_mul_f32 v[122:123], v[122:123], v[138:139]
	v_mul_f32_e32 v118, v118, v138
	v_cvt_pk_bf16_f32 v122, v122, v123
	v_mul_f32_e32 v119, v119, v139
	v_cvt_pk_bf16_f32 v118, v118, v119
	v_mul_f32_e32 v114, v114, v138
	v_mul_f32_e32 v115, v115, v139
	s_waitcnt vmcnt(0) lgkmcnt(0)
	v_ffbh_u32_e32 v123, v147
	v_min_u32_e32 v123, 32, v123
	v_lshlrev_b64 v[146:147], v123, v[146:147]
	v_min_u32_e32 v146, 1, v146
	v_or_b32_e32 v146, v147, v146
	v_cvt_f32_u32_e32 v146, v146
	v_sub_u32_e32 v123, 32, v123
	v_ldexp_f32 v147, v146, v123
	v_ffbh_u32_e32 v123, v145
	v_min_u32_e32 v123, 32, v123
	v_lshlrev_b64 v[144:145], v123, v[144:145]
	v_min_u32_e32 v144, 1, v144
	v_or_b32_e32 v144, v145, v144
	v_cvt_f32_u32_e32 v144, v144
	v_sub_u32_e32 v123, 32, v123
	v_ldexp_f32 v146, v144, v123
	v_pk_fma_f32 v[144:145], v[146:147], s[0:1], v[136:137] op_sel_hi:[1,0,0]
	s_nop 0
	v_mul_f32_e32 v123, 0x4b800000, v144
	v_cmp_gt_f32_e64 s[4:5], s33, v144
	v_cmp_gt_f32_e32 vcc, s33, v145
	s_nop 0
	v_cndmask_b32_e64 v123, v144, v123, s[4:5]
	v_rsq_f32_e32 v144, v123
	v_mul_f32_e32 v123, 0x4b800000, v145
	v_cndmask_b32_e32 v123, v145, v123, vcc
	v_rsq_f32_e32 v145, v123
	s_nop 0
	v_pk_mul_f32 v[146:147], v[144:145], s[2:3] op_sel_hi:[1,0]
	s_nop 0
	v_cndmask_b32_e32 v145, v145, v147, vcc
	v_cndmask_b32_e64 v144, v144, v146, s[4:5]
	v_pk_mul_f32 v[124:125], v[124:125], v[144:145]
	v_mul_f32_e32 v120, v120, v144
	v_mul_f32_e32 v121, v121, v145
	v_cvt_pk_bf16_f32 v123, v124, v125
	v_mad_u32_u24 v124, v0, s72, v148
	v_cvt_pk_bf16_f32 v119, v120, v121
	ds_write_b64 v124, v[118:119] offset:8448
	v_mul_f32_e32 v118, v126, v138
	v_mul_f32_e32 v119, v127, v139
	v_cvt_pk_bf16_f32 v120, v118, v119
	v_mov_b32_e32 v118, 0x10800
	ds_write_b64 v124, v[122:123]
	v_mul_f32_e32 v121, v128, v144
	v_mul_f32_e32 v122, v129, v145
	v_mad_u32_u24 v118, v0, s72, v118
	v_cvt_pk_bf16_f32 v121, v121, v122
	v_add_u32_e32 v119, v148, v118
	ds_write_b64 v119, v[120:121]
	v_mul_f32_e32 v119, v116, v144
	v_cvt_pk_bf16_f32 v116, v114, v115
	v_mov_b32_e32 v114, 0x12900
	v_mul_f32_e32 v117, v117, v145
	v_mad_u32_u24 v114, v0, s72, v114
	v_cvt_pk_bf16_f32 v117, v119, v117
	v_add_u32_e32 v115, v148, v114
	ds_write_b64 v115, v[116:117]
	v_or_b32_e32 v115, 16, v143
	v_add_u32_e32 v116, v142, v115
	v_ashrrev_i32_e32 v117, 31, v116
	v_lshl_add_u64 v[116:117], v[116:117], 3, v[130:131]
	flat_load_dwordx4 v[120:123], v[116:117]
	v_lshl_or_b32 v115, v115, 1, v141
	s_waitcnt vmcnt(0) lgkmcnt(0)
	v_ffbh_u32_e32 v119, v123
	v_min_u32_e32 v119, 32, v119
	v_lshlrev_b64 v[122:123], v119, v[122:123]
	v_min_u32_e32 v122, 1, v122
	v_or_b32_e32 v122, v123, v122
	v_cvt_f32_u32_e32 v122, v122
	v_sub_u32_e32 v119, 32, v119
	v_ldexp_f32 v123, v122, v119
	v_ffbh_u32_e32 v119, v121
	v_min_u32_e32 v119, 32, v119
	v_lshlrev_b64 v[120:121], v119, v[120:121]
	v_min_u32_e32 v120, 1, v120
	v_or_b32_e32 v120, v121, v120
	v_cvt_f32_u32_e32 v120, v120
	v_sub_u32_e32 v119, 32, v119
	v_ldexp_f32 v122, v120, v119
	v_pk_fma_f32 v[120:121], v[122:123], s[0:1], v[136:137] op_sel_hi:[1,0,0]
	s_nop 0
	v_mul_f32_e32 v119, 0x4b800000, v120
	v_cmp_gt_f32_e64 s[4:5], s33, v120
	v_cmp_gt_f32_e32 vcc, s33, v121
	s_nop 0
	v_cndmask_b32_e64 v119, v120, v119, s[4:5]
	v_rsq_f32_e32 v120, v119
	v_mul_f32_e32 v119, 0x4b800000, v121
	v_cndmask_b32_e32 v119, v121, v119, vcc
	v_rsq_f32_e32 v121, v119
	s_nop 0
	v_pk_mul_f32 v[122:123], v[120:121], s[2:3] op_sel_hi:[1,0]
	s_nop 0
	v_cndmask_b32_e32 v125, v121, v123, vcc
	v_cndmask_b32_e64 v124, v120, v122, s[4:5]
	flat_load_dwordx4 v[120:123], v[116:117] offset:16
	v_pk_mul_f32 v[102:103], v[102:103], v[124:125]
	v_mul_f32_e32 v98, v98, v124
	v_cvt_pk_bf16_f32 v102, v102, v103
	v_mul_f32_e32 v99, v99, v125
	v_cvt_pk_bf16_f32 v98, v98, v99
	s_waitcnt vmcnt(0) lgkmcnt(0)
	v_ffbh_u32_e32 v103, v123
	v_min_u32_e32 v103, 32, v103
	v_lshlrev_b64 v[116:117], v103, v[122:123]
	v_min_u32_e32 v116, 1, v116
	v_or_b32_e32 v116, v117, v116
	v_cvt_f32_u32_e32 v116, v116
	v_sub_u32_e32 v103, 32, v103
	v_ldexp_f32 v117, v116, v103
	v_ffbh_u32_e32 v103, v121
	v_min_u32_e32 v103, 32, v103
	v_lshlrev_b64 v[120:121], v103, v[120:121]
	v_min_u32_e32 v116, 1, v120
	v_or_b32_e32 v116, v121, v116
	v_cvt_f32_u32_e32 v116, v116
	v_sub_u32_e32 v103, 32, v103
	v_ldexp_f32 v116, v116, v103
	v_pk_fma_f32 v[116:117], v[116:117], s[0:1], v[136:137] op_sel_hi:[1,0,0]
	s_nop 0
	v_mul_f32_e32 v103, 0x4b800000, v116
	v_cmp_gt_f32_e64 s[4:5], s33, v116
	v_cmp_gt_f32_e32 vcc, s33, v117
	s_nop 0
	v_cndmask_b32_e64 v103, v116, v103, s[4:5]
	v_rsq_f32_e32 v116, v103
	v_mul_f32_e32 v103, 0x4b800000, v117
	v_cndmask_b32_e32 v103, v117, v103, vcc
	v_rsq_f32_e32 v117, v103
	s_nop 0
	v_pk_mul_f32 v[120:121], v[116:117], s[2:3] op_sel_hi:[1,0]
	s_nop 0
	v_cndmask_b32_e32 v117, v117, v121, vcc
	v_cndmask_b32_e64 v116, v116, v120, s[4:5]
	v_pk_mul_f32 v[104:105], v[104:105], v[116:117]
	v_mul_f32_e32 v100, v100, v116
	v_mul_f32_e32 v101, v101, v117
	v_cvt_pk_bf16_f32 v103, v104, v105
	v_mad_u32_u24 v104, v0, s72, v115
	v_cvt_pk_bf16_f32 v99, v100, v101
	ds_write_b64 v104, v[98:99] offset:8448
	v_mul_f32_e32 v98, v110, v124
	v_mul_f32_e32 v99, v111, v125
	v_mul_f32_e32 v100, v112, v116
	v_mul_f32_e32 v101, v113, v117
	v_cvt_pk_bf16_f32 v98, v98, v99
	v_cvt_pk_bf16_f32 v99, v100, v101
	v_add_u32_e32 v100, v115, v118
	ds_write_b64 v100, v[98:99]
	v_mul_f32_e32 v98, v106, v124
	v_mul_f32_e32 v99, v107, v125
	v_mul_f32_e32 v100, v108, v116
	v_mul_f32_e32 v101, v109, v117
	v_cvt_pk_bf16_f32 v98, v98, v99
	v_cvt_pk_bf16_f32 v99, v100, v101
	v_add_u32_e32 v100, v115, v114
	ds_write_b64 v100, v[98:99]
	v_or_b32_e32 v100, 32, v143
	v_add_u32_e32 v98, v142, v100
	v_ashrrev_i32_e32 v99, 31, v98
	ds_write_b64 v104, v[102:103]
	v_lshl_add_u64 v[98:99], v[98:99], 3, v[130:131]
	v_lshl_or_b32 v104, v100, 1, v141
	flat_load_dwordx4 v[100:103], v[98:99]
	s_waitcnt vmcnt(0) lgkmcnt(0)
	v_ffbh_u32_e32 v105, v103
	v_min_u32_e32 v105, 32, v105
	v_lshlrev_b64 v[102:103], v105, v[102:103]
	v_min_u32_e32 v102, 1, v102
	v_or_b32_e32 v102, v103, v102
	v_cvt_f32_u32_e32 v102, v102
	v_sub_u32_e32 v103, 32, v105
	v_ldexp_f32 v103, v102, v103
	v_ffbh_u32_e32 v102, v101
	v_min_u32_e32 v102, 32, v102
	v_lshlrev_b64 v[100:101], v102, v[100:101]
	v_min_u32_e32 v100, 1, v100
	v_or_b32_e32 v100, v101, v100
	v_cvt_f32_u32_e32 v100, v100
	v_sub_u32_e32 v101, 32, v102
	v_ldexp_f32 v102, v100, v101
	v_pk_fma_f32 v[100:101], v[102:103], s[0:1], v[136:137] op_sel_hi:[1,0,0]
	s_nop 0
	v_mul_f32_e32 v102, 0x4b800000, v100
	v_cmp_gt_f32_e64 s[4:5], s33, v100
	v_cmp_gt_f32_e32 vcc, s33, v101
	s_nop 0
	v_cndmask_b32_e64 v100, v100, v102, s[4:5]
	v_mul_f32_e32 v102, 0x4b800000, v101
	v_cndmask_b32_e32 v101, v101, v102, vcc
	v_rsq_f32_e32 v100, v100
	v_rsq_f32_e32 v101, v101
	s_nop 0
	v_pk_mul_f32 v[102:103], v[100:101], s[2:3] op_sel_hi:[1,0]
	s_nop 0
	v_cndmask_b32_e32 v103, v101, v103, vcc
	v_cndmask_b32_e64 v102, v100, v102, s[4:5]
	flat_load_dwordx4 v[98:101], v[98:99] offset:16
	v_pk_mul_f32 v[86:87], v[86:87], v[102:103]
	v_mul_f32_e32 v82, v82, v102
	v_cvt_pk_bf16_f32 v86, v86, v87
	v_mul_f32_e32 v83, v83, v103
	v_cvt_pk_bf16_f32 v82, v82, v83
	s_waitcnt vmcnt(0) lgkmcnt(0)
	v_ffbh_u32_e32 v87, v101
	v_min_u32_e32 v87, 32, v87
	v_lshlrev_b64 v[100:101], v87, v[100:101]
	v_min_u32_e32 v100, 1, v100
	v_or_b32_e32 v100, v101, v100
	v_cvt_f32_u32_e32 v100, v100
	v_sub_u32_e32 v87, 32, v87
	v_ldexp_f32 v101, v100, v87
	v_ffbh_u32_e32 v87, v99
	v_min_u32_e32 v87, 32, v87
	v_lshlrev_b64 v[98:99], v87, v[98:99]
	v_min_u32_e32 v98, 1, v98
	v_or_b32_e32 v98, v99, v98
	v_cvt_f32_u32_e32 v98, v98
	v_sub_u32_e32 v87, 32, v87
	v_ldexp_f32 v100, v98, v87
	v_pk_fma_f32 v[98:99], v[100:101], s[0:1], v[136:137] op_sel_hi:[1,0,0]
	s_nop 0
	v_mul_f32_e32 v87, 0x4b800000, v98
	v_cmp_gt_f32_e64 s[4:5], s33, v98
	v_cmp_gt_f32_e32 vcc, s33, v99
	s_nop 0
	v_cndmask_b32_e64 v87, v98, v87, s[4:5]
	v_rsq_f32_e32 v98, v87
	v_mul_f32_e32 v87, 0x4b800000, v99
	v_cndmask_b32_e32 v87, v99, v87, vcc
	v_rsq_f32_e32 v99, v87
	s_nop 0
	v_pk_mul_f32 v[100:101], v[98:99], s[2:3] op_sel_hi:[1,0]
	s_nop 0
	v_cndmask_b32_e32 v99, v99, v101, vcc
	v_cndmask_b32_e64 v98, v98, v100, s[4:5]
	v_pk_mul_f32 v[88:89], v[88:89], v[98:99]
	v_mul_f32_e32 v84, v84, v98
	v_mul_f32_e32 v85, v85, v99
	v_cvt_pk_bf16_f32 v87, v88, v89
	v_mad_u32_u24 v88, v0, s72, v104
	v_cvt_pk_bf16_f32 v83, v84, v85
	ds_write_b64 v88, v[82:83] offset:8448
	v_mul_f32_e32 v82, v94, v102
	v_mul_f32_e32 v83, v95, v103
	v_mul_f32_e32 v84, v96, v98
	v_mul_f32_e32 v85, v97, v99
	v_cvt_pk_bf16_f32 v82, v82, v83
	v_cvt_pk_bf16_f32 v83, v84, v85
	v_add_u32_e32 v84, v104, v118
	ds_write_b64 v84, v[82:83]
	v_mul_f32_e32 v82, v90, v102
	v_mul_f32_e32 v83, v91, v103
	v_mul_f32_e32 v84, v92, v98
	v_mul_f32_e32 v85, v93, v99
	v_cvt_pk_bf16_f32 v82, v82, v83
	v_cvt_pk_bf16_f32 v83, v84, v85
	v_add_u32_e32 v84, v104, v114
	ds_write_b64 v84, v[82:83]
	v_or_b32_e32 v84, 48, v143
	v_add_u32_e32 v82, v142, v84
	v_ashrrev_i32_e32 v83, 31, v82
	ds_write_b64 v88, v[86:87]
	v_lshl_add_u64 v[82:83], v[82:83], 3, v[130:131]
	v_lshl_or_b32 v88, v84, 1, v141
	flat_load_dwordx4 v[84:87], v[82:83]
	s_waitcnt vmcnt(0) lgkmcnt(0)
	v_ffbh_u32_e32 v89, v87
	v_min_u32_e32 v89, 32, v89
	v_lshlrev_b64 v[86:87], v89, v[86:87]
	v_min_u32_e32 v86, 1, v86
	v_or_b32_e32 v86, v87, v86
	v_cvt_f32_u32_e32 v86, v86
	v_sub_u32_e32 v87, 32, v89
	v_ldexp_f32 v87, v86, v87
	v_ffbh_u32_e32 v86, v85
	v_min_u32_e32 v86, 32, v86
	v_lshlrev_b64 v[84:85], v86, v[84:85]
	v_min_u32_e32 v84, 1, v84
	v_or_b32_e32 v84, v85, v84
	v_cvt_f32_u32_e32 v84, v84
	v_sub_u32_e32 v85, 32, v86
	v_ldexp_f32 v86, v84, v85
	v_pk_fma_f32 v[84:85], v[86:87], s[0:1], v[136:137] op_sel_hi:[1,0,0]
	s_nop 0
	v_mul_f32_e32 v86, 0x4b800000, v84
	v_cmp_gt_f32_e64 s[4:5], s33, v84
	v_cmp_gt_f32_e32 vcc, s33, v85
	s_nop 0
	v_cndmask_b32_e64 v84, v84, v86, s[4:5]
	v_mul_f32_e32 v86, 0x4b800000, v85
	v_cndmask_b32_e32 v85, v85, v86, vcc
	v_rsq_f32_e32 v84, v84
	v_rsq_f32_e32 v85, v85
	s_nop 0
	v_pk_mul_f32 v[86:87], v[84:85], s[2:3] op_sel_hi:[1,0]
	s_nop 0
	v_cndmask_b32_e32 v87, v85, v87, vcc
	v_cndmask_b32_e64 v86, v84, v86, s[4:5]
	flat_load_dwordx4 v[82:85], v[82:83] offset:16
	v_pk_mul_f32 v[70:71], v[70:71], v[86:87]
	v_mul_f32_e32 v66, v66, v86
	v_cvt_pk_bf16_f32 v70, v70, v71
	v_mul_f32_e32 v67, v67, v87
	v_cvt_pk_bf16_f32 v66, v66, v67
	s_waitcnt vmcnt(0) lgkmcnt(0)
	v_ffbh_u32_e32 v71, v85
	v_min_u32_e32 v71, 32, v71
	v_lshlrev_b64 v[84:85], v71, v[84:85]
	v_min_u32_e32 v84, 1, v84
	v_or_b32_e32 v84, v85, v84
	v_cvt_f32_u32_e32 v84, v84
	v_sub_u32_e32 v71, 32, v71
	v_ldexp_f32 v85, v84, v71
	v_ffbh_u32_e32 v71, v83
	v_min_u32_e32 v71, 32, v71
	v_lshlrev_b64 v[82:83], v71, v[82:83]
	v_min_u32_e32 v82, 1, v82
	v_or_b32_e32 v82, v83, v82
	v_cvt_f32_u32_e32 v82, v82
	v_sub_u32_e32 v71, 32, v71
	v_ldexp_f32 v84, v82, v71
	v_pk_fma_f32 v[82:83], v[84:85], s[0:1], v[136:137] op_sel_hi:[1,0,0]
	s_nop 0
	v_mul_f32_e32 v71, 0x4b800000, v82
	v_cmp_gt_f32_e64 s[4:5], s33, v82
	v_cmp_gt_f32_e32 vcc, s33, v83
	s_nop 0
	v_cndmask_b32_e64 v71, v82, v71, s[4:5]
	v_rsq_f32_e32 v82, v71
	v_mul_f32_e32 v71, 0x4b800000, v83
	v_cndmask_b32_e32 v71, v83, v71, vcc
	v_rsq_f32_e32 v83, v71
	s_nop 0
	v_pk_mul_f32 v[84:85], v[82:83], s[2:3] op_sel_hi:[1,0]
	s_nop 0
	v_cndmask_b32_e32 v83, v83, v85, vcc
	v_cndmask_b32_e64 v82, v82, v84, s[4:5]
	v_pk_mul_f32 v[72:73], v[72:73], v[82:83]
	v_mul_f32_e32 v68, v68, v82
	v_mul_f32_e32 v69, v69, v83
	v_cvt_pk_bf16_f32 v71, v72, v73
	v_mad_u32_u24 v72, v0, s72, v88
	v_cvt_pk_bf16_f32 v67, v68, v69
	ds_write_b64 v72, v[66:67] offset:8448
	v_mul_f32_e32 v66, v78, v86
	v_mul_f32_e32 v67, v79, v87
	v_mul_f32_e32 v68, v80, v82
	v_mul_f32_e32 v69, v81, v83
	v_cvt_pk_bf16_f32 v66, v66, v67
	v_cvt_pk_bf16_f32 v67, v68, v69
	v_add_u32_e32 v68, v88, v118
	ds_write_b64 v68, v[66:67]
	v_mul_f32_e32 v66, v74, v86
	v_mul_f32_e32 v67, v75, v87
	v_mul_f32_e32 v68, v76, v82
	v_mul_f32_e32 v69, v77, v83
	v_cvt_pk_bf16_f32 v66, v66, v67
	v_cvt_pk_bf16_f32 v67, v68, v69
	v_add_u32_e32 v68, v88, v114
	ds_write_b64 v68, v[66:67]
	v_add_u32_e32 v68, 0x80, v143
	v_add_u32_e32 v66, v142, v68
	v_ashrrev_i32_e32 v67, 31, v66
	ds_write_b64 v72, v[70:71]
	v_lshl_add_u64 v[66:67], v[66:67], 3, v[130:131]
	v_lshl_or_b32 v72, v68, 1, v141
	flat_load_dwordx4 v[68:71], v[66:67]
	s_waitcnt vmcnt(0) lgkmcnt(0)
	v_ffbh_u32_e32 v73, v71
	v_min_u32_e32 v73, 32, v73
	v_lshlrev_b64 v[70:71], v73, v[70:71]
	v_min_u32_e32 v70, 1, v70
	v_or_b32_e32 v70, v71, v70
	v_cvt_f32_u32_e32 v70, v70
	v_sub_u32_e32 v71, 32, v73
	v_ldexp_f32 v71, v70, v71
	v_ffbh_u32_e32 v70, v69
	v_min_u32_e32 v70, 32, v70
	v_lshlrev_b64 v[68:69], v70, v[68:69]
	v_min_u32_e32 v68, 1, v68
	v_or_b32_e32 v68, v69, v68
	v_cvt_f32_u32_e32 v68, v68
	v_sub_u32_e32 v69, 32, v70
	v_ldexp_f32 v70, v68, v69
	v_pk_fma_f32 v[68:69], v[70:71], s[0:1], v[136:137] op_sel_hi:[1,0,0]
	s_nop 0
	v_mul_f32_e32 v70, 0x4b800000, v68
	v_cmp_gt_f32_e64 s[4:5], s33, v68
	v_cmp_gt_f32_e32 vcc, s33, v69
	s_nop 0
	v_cndmask_b32_e64 v68, v68, v70, s[4:5]
	v_mul_f32_e32 v70, 0x4b800000, v69
	v_cndmask_b32_e32 v69, v69, v70, vcc
	v_rsq_f32_e32 v68, v68
	v_rsq_f32_e32 v69, v69
	s_nop 0
	v_pk_mul_f32 v[70:71], v[68:69], s[2:3] op_sel_hi:[1,0]
	s_nop 0
	v_cndmask_b32_e32 v71, v69, v71, vcc
	v_cndmask_b32_e64 v70, v68, v70, s[4:5]
	flat_load_dwordx4 v[66:69], v[66:67] offset:16
	v_pk_mul_f32 v[58:59], v[58:59], v[70:71]
	v_mul_f32_e32 v50, v50, v70
	v_cvt_pk_bf16_f32 v58, v58, v59
	v_mul_f32_e32 v51, v51, v71
	v_cvt_pk_bf16_f32 v50, v50, v51
	s_waitcnt vmcnt(0) lgkmcnt(0)
	v_ffbh_u32_e32 v59, v69
	v_min_u32_e32 v59, 32, v59
	v_lshlrev_b64 v[68:69], v59, v[68:69]
	v_min_u32_e32 v68, 1, v68
	v_or_b32_e32 v68, v69, v68
	v_cvt_f32_u32_e32 v68, v68
	v_sub_u32_e32 v59, 32, v59
	v_ldexp_f32 v69, v68, v59
	v_ffbh_u32_e32 v59, v67
	v_min_u32_e32 v59, 32, v59
	v_lshlrev_b64 v[66:67], v59, v[66:67]
	v_min_u32_e32 v66, 1, v66
	v_or_b32_e32 v66, v67, v66
	v_cvt_f32_u32_e32 v66, v66
	v_sub_u32_e32 v59, 32, v59
	v_ldexp_f32 v68, v66, v59
	v_pk_fma_f32 v[66:67], v[68:69], s[0:1], v[136:137] op_sel_hi:[1,0,0]
	s_nop 0
	v_mul_f32_e32 v59, 0x4b800000, v66
	v_cmp_gt_f32_e64 s[4:5], s33, v66
	v_cmp_gt_f32_e32 vcc, s33, v67
	s_nop 0
	v_cndmask_b32_e64 v59, v66, v59, s[4:5]
	v_rsq_f32_e32 v66, v59
	v_mul_f32_e32 v59, 0x4b800000, v67
	v_cndmask_b32_e32 v59, v67, v59, vcc
	v_rsq_f32_e32 v67, v59
	s_nop 0
	v_pk_mul_f32 v[68:69], v[66:67], s[2:3] op_sel_hi:[1,0]
	s_nop 0
	v_cndmask_b32_e32 v67, v67, v69, vcc
	v_cndmask_b32_e64 v66, v66, v68, s[4:5]
	v_pk_mul_f32 v[60:61], v[60:61], v[66:67]
	v_mul_f32_e32 v52, v52, v66
	v_mul_f32_e32 v53, v53, v67
	v_cvt_pk_bf16_f32 v59, v60, v61
	v_mad_u32_u24 v60, v0, s72, v72
	v_cvt_pk_bf16_f32 v51, v52, v53
	ds_write_b64 v60, v[50:51] offset:8448
	v_mul_f32_e32 v50, v62, v70
	v_mul_f32_e32 v51, v63, v71
	v_mul_f32_e32 v52, v64, v66
	v_mul_f32_e32 v53, v65, v67
	v_cvt_pk_bf16_f32 v50, v50, v51
	v_cvt_pk_bf16_f32 v51, v52, v53
	v_add_u32_e32 v52, v72, v118
	ds_write_b64 v52, v[50:51]
	v_mul_f32_e32 v50, v54, v70
	v_mul_f32_e32 v51, v55, v71
	v_mul_f32_e32 v52, v56, v66
	v_mul_f32_e32 v53, v57, v67
	v_cvt_pk_bf16_f32 v50, v50, v51
	v_cvt_pk_bf16_f32 v51, v52, v53
	v_add_u32_e32 v52, v72, v114
	ds_write_b64 v52, v[50:51]
	v_add_u32_e32 v52, 0x90, v143
	v_add_u32_e32 v50, v142, v52
	v_ashrrev_i32_e32 v51, 31, v50
	ds_write_b64 v60, v[58:59]
	v_lshl_add_u64 v[50:51], v[50:51], 3, v[130:131]
	v_lshl_or_b32 v56, v52, 1, v141
	flat_load_dwordx4 v[52:55], v[50:51]
	s_waitcnt vmcnt(0) lgkmcnt(0)
	v_ffbh_u32_e32 v57, v55
	v_min_u32_e32 v57, 32, v57
	v_lshlrev_b64 v[54:55], v57, v[54:55]
	v_min_u32_e32 v54, 1, v54
	v_or_b32_e32 v54, v55, v54
	v_cvt_f32_u32_e32 v54, v54
	v_sub_u32_e32 v55, 32, v57
	v_ldexp_f32 v55, v54, v55
	v_ffbh_u32_e32 v54, v53
	v_min_u32_e32 v54, 32, v54
	v_lshlrev_b64 v[52:53], v54, v[52:53]
	v_min_u32_e32 v52, 1, v52
	v_or_b32_e32 v52, v53, v52
	v_cvt_f32_u32_e32 v52, v52
	v_sub_u32_e32 v53, 32, v54
	v_ldexp_f32 v54, v52, v53
	v_pk_fma_f32 v[52:53], v[54:55], s[0:1], v[136:137] op_sel_hi:[1,0,0]
	s_nop 0
	v_mul_f32_e32 v54, 0x4b800000, v52
	v_cmp_gt_f32_e64 s[4:5], s33, v52
	v_cmp_gt_f32_e32 vcc, s33, v53
	s_nop 0
	v_cndmask_b32_e64 v52, v52, v54, s[4:5]
	v_mul_f32_e32 v54, 0x4b800000, v53
	v_cndmask_b32_e32 v53, v53, v54, vcc
	v_rsq_f32_e32 v52, v52
	v_rsq_f32_e32 v53, v53
	s_nop 0
	v_pk_mul_f32 v[54:55], v[52:53], s[2:3] op_sel_hi:[1,0]
	s_nop 0
	v_cndmask_b32_e32 v55, v53, v55, vcc
	v_cndmask_b32_e64 v54, v52, v54, s[4:5]
	flat_load_dwordx4 v[50:53], v[50:51] offset:16
	v_pk_mul_f32 v[42:43], v[42:43], v[54:55]
	v_mul_f32_e32 v34, v34, v54
	v_cvt_pk_bf16_f32 v42, v42, v43
	v_mul_f32_e32 v35, v35, v55
	v_cvt_pk_bf16_f32 v34, v34, v35
	s_waitcnt vmcnt(0) lgkmcnt(0)
	v_ffbh_u32_e32 v43, v53
	v_min_u32_e32 v43, 32, v43
	v_lshlrev_b64 v[52:53], v43, v[52:53]
	v_min_u32_e32 v52, 1, v52
	v_or_b32_e32 v52, v53, v52
	v_cvt_f32_u32_e32 v52, v52
	v_sub_u32_e32 v43, 32, v43
	v_ldexp_f32 v53, v52, v43
	v_ffbh_u32_e32 v43, v51
	v_min_u32_e32 v43, 32, v43
	v_lshlrev_b64 v[50:51], v43, v[50:51]
	v_min_u32_e32 v50, 1, v50
	v_or_b32_e32 v50, v51, v50
	v_cvt_f32_u32_e32 v50, v50
	v_sub_u32_e32 v43, 32, v43
	v_ldexp_f32 v52, v50, v43
	v_pk_fma_f32 v[50:51], v[52:53], s[0:1], v[136:137] op_sel_hi:[1,0,0]
	s_nop 0
	v_mul_f32_e32 v43, 0x4b800000, v50
	v_cmp_gt_f32_e64 s[4:5], s33, v50
	v_cmp_gt_f32_e32 vcc, s33, v51
	s_nop 0
	v_cndmask_b32_e64 v43, v50, v43, s[4:5]
	v_rsq_f32_e32 v50, v43
	v_mul_f32_e32 v43, 0x4b800000, v51
	v_cndmask_b32_e32 v43, v51, v43, vcc
	v_rsq_f32_e32 v51, v43
	s_nop 0
	v_pk_mul_f32 v[52:53], v[50:51], s[2:3] op_sel_hi:[1,0]
	s_nop 0
	v_cndmask_b32_e32 v51, v51, v53, vcc
	v_cndmask_b32_e64 v50, v50, v52, s[4:5]
	v_pk_mul_f32 v[44:45], v[44:45], v[50:51]
	v_mul_f32_e32 v36, v36, v50
	v_mul_f32_e32 v37, v37, v51
	v_cvt_pk_bf16_f32 v43, v44, v45
	v_mad_u32_u24 v44, v0, s72, v56
	v_cvt_pk_bf16_f32 v35, v36, v37
	ds_write_b64 v44, v[34:35] offset:8448
	v_mul_f32_e32 v34, v46, v54
	v_mul_f32_e32 v35, v47, v55
	v_mul_f32_e32 v36, v48, v50
	v_mul_f32_e32 v37, v49, v51
	v_cvt_pk_bf16_f32 v34, v34, v35
	v_cvt_pk_bf16_f32 v35, v36, v37
	v_add_u32_e32 v36, v56, v118
	ds_write_b64 v36, v[34:35]
	v_mul_f32_e32 v34, v38, v54
	v_mul_f32_e32 v35, v39, v55
	v_mul_f32_e32 v36, v40, v50
	v_mul_f32_e32 v37, v41, v51
	v_cvt_pk_bf16_f32 v34, v34, v35
	v_cvt_pk_bf16_f32 v35, v36, v37
	v_add_u32_e32 v36, v56, v114
	ds_write_b64 v36, v[34:35]
	v_add_u32_e32 v36, 0xa0, v143
	v_add_u32_e32 v34, v142, v36
	v_ashrrev_i32_e32 v35, 31, v34
	ds_write_b64 v44, v[42:43]
	v_lshl_add_u64 v[34:35], v[34:35], 3, v[130:131]
	v_lshl_or_b32 v40, v36, 1, v141
	flat_load_dwordx4 v[36:39], v[34:35]
	s_waitcnt vmcnt(0) lgkmcnt(0)
	v_ffbh_u32_e32 v41, v39
	v_min_u32_e32 v41, 32, v41
	v_lshlrev_b64 v[38:39], v41, v[38:39]
	v_min_u32_e32 v38, 1, v38
	v_or_b32_e32 v38, v39, v38
	v_cvt_f32_u32_e32 v38, v38
	v_sub_u32_e32 v39, 32, v41
	v_ldexp_f32 v39, v38, v39
	v_ffbh_u32_e32 v38, v37
	v_min_u32_e32 v38, 32, v38
	v_lshlrev_b64 v[36:37], v38, v[36:37]
	v_min_u32_e32 v36, 1, v36
	v_or_b32_e32 v36, v37, v36
	v_cvt_f32_u32_e32 v36, v36
	v_sub_u32_e32 v37, 32, v38
	v_ldexp_f32 v38, v36, v37
	v_pk_fma_f32 v[36:37], v[38:39], s[0:1], v[136:137] op_sel_hi:[1,0,0]
	s_nop 0
	v_mul_f32_e32 v38, 0x4b800000, v36
	v_cmp_gt_f32_e64 s[4:5], s33, v36
	v_cmp_gt_f32_e32 vcc, s33, v37
	s_nop 0
	v_cndmask_b32_e64 v36, v36, v38, s[4:5]
	v_mul_f32_e32 v38, 0x4b800000, v37
	v_cndmask_b32_e32 v37, v37, v38, vcc
	v_rsq_f32_e32 v36, v36
	v_rsq_f32_e32 v37, v37
	s_nop 0
	v_pk_mul_f32 v[38:39], v[36:37], s[2:3] op_sel_hi:[1,0]
	s_nop 0
	v_cndmask_b32_e32 v39, v37, v39, vcc
	v_cndmask_b32_e64 v38, v36, v38, s[4:5]
	flat_load_dwordx4 v[34:37], v[34:35] offset:16
	v_pk_mul_f32 v[26:27], v[26:27], v[38:39]
	v_mul_f32_e32 v18, v18, v38
	v_cvt_pk_bf16_f32 v26, v26, v27
	v_mul_f32_e32 v19, v19, v39
	v_cvt_pk_bf16_f32 v18, v18, v19
	s_waitcnt vmcnt(0) lgkmcnt(0)
	v_ffbh_u32_e32 v27, v37
	v_min_u32_e32 v27, 32, v27
	v_lshlrev_b64 v[36:37], v27, v[36:37]
	v_min_u32_e32 v36, 1, v36
	v_or_b32_e32 v36, v37, v36
	v_cvt_f32_u32_e32 v36, v36
	v_sub_u32_e32 v27, 32, v27
	v_ldexp_f32 v37, v36, v27
	v_ffbh_u32_e32 v27, v35
	v_min_u32_e32 v27, 32, v27
	v_lshlrev_b64 v[34:35], v27, v[34:35]
	v_min_u32_e32 v34, 1, v34
	v_or_b32_e32 v34, v35, v34
	v_cvt_f32_u32_e32 v34, v34
	v_sub_u32_e32 v27, 32, v27
	v_ldexp_f32 v36, v34, v27
	v_pk_fma_f32 v[34:35], v[36:37], s[0:1], v[136:137] op_sel_hi:[1,0,0]
	s_nop 0
	v_mul_f32_e32 v27, 0x4b800000, v34
	v_cmp_gt_f32_e64 s[4:5], s33, v34
	v_cmp_gt_f32_e32 vcc, s33, v35
	s_nop 0
	v_cndmask_b32_e64 v27, v34, v27, s[4:5]
	v_rsq_f32_e32 v34, v27
	v_mul_f32_e32 v27, 0x4b800000, v35
	v_cndmask_b32_e32 v27, v35, v27, vcc
	v_rsq_f32_e32 v35, v27
	s_nop 0
	v_pk_mul_f32 v[36:37], v[34:35], s[2:3] op_sel_hi:[1,0]
	s_nop 0
	v_cndmask_b32_e32 v35, v35, v37, vcc
	v_cndmask_b32_e64 v34, v34, v36, s[4:5]
	v_pk_mul_f32 v[28:29], v[28:29], v[34:35]
	v_mul_f32_e32 v20, v20, v34
	v_mul_f32_e32 v21, v21, v35
	v_cvt_pk_bf16_f32 v27, v28, v29
	v_mad_u32_u24 v28, v0, s72, v40
	v_cvt_pk_bf16_f32 v19, v20, v21
	ds_write_b64 v28, v[18:19] offset:8448
	v_mul_f32_e32 v18, v30, v38
	v_mul_f32_e32 v19, v31, v39
	v_mul_f32_e32 v20, v32, v34
	v_mul_f32_e32 v21, v33, v35
	v_cvt_pk_bf16_f32 v18, v18, v19
	v_cvt_pk_bf16_f32 v19, v20, v21
	v_add_u32_e32 v20, v40, v118
	ds_write_b64 v20, v[18:19]
	v_mul_f32_e32 v18, v22, v38
	v_mul_f32_e32 v19, v23, v39
	v_mul_f32_e32 v20, v24, v34
	v_mul_f32_e32 v21, v25, v35
	v_cvt_pk_bf16_f32 v18, v18, v19
	v_cvt_pk_bf16_f32 v19, v20, v21
	v_add_u32_e32 v20, v40, v114
	ds_write_b64 v20, v[18:19]
	v_add_u32_e32 v20, 0xb0, v143
	v_add_u32_e32 v18, v142, v20
	v_ashrrev_i32_e32 v19, 31, v18
	ds_write_b64 v28, v[26:27]
	v_lshl_add_u64 v[18:19], v[18:19], 3, v[130:131]
	v_lshl_or_b32 v24, v20, 1, v141
	flat_load_dwordx4 v[20:23], v[18:19]
	v_mad_u32_u24 v0, v0, s72, v24
	s_waitcnt vmcnt(0) lgkmcnt(0)
	v_ffbh_u32_e32 v25, v23
	v_min_u32_e32 v25, 32, v25
	v_lshlrev_b64 v[22:23], v25, v[22:23]
	v_min_u32_e32 v22, 1, v22
	v_or_b32_e32 v22, v23, v22
	v_cvt_f32_u32_e32 v22, v22
	v_sub_u32_e32 v23, 32, v25
	v_ldexp_f32 v23, v22, v23
	v_ffbh_u32_e32 v22, v21
	v_min_u32_e32 v22, 32, v22
	v_lshlrev_b64 v[20:21], v22, v[20:21]
	v_min_u32_e32 v20, 1, v20
	v_or_b32_e32 v20, v21, v20
	v_cvt_f32_u32_e32 v20, v20
	v_sub_u32_e32 v21, 32, v22
	v_ldexp_f32 v22, v20, v21
	v_pk_fma_f32 v[20:21], v[22:23], s[0:1], v[136:137] op_sel_hi:[1,0,0]
	s_nop 0
	v_mul_f32_e32 v22, 0x4b800000, v20
	v_cmp_gt_f32_e64 s[4:5], s33, v20
	v_cmp_gt_f32_e32 vcc, s33, v21
	s_nop 0
	v_cndmask_b32_e64 v20, v20, v22, s[4:5]
	v_mul_f32_e32 v22, 0x4b800000, v21
	v_cndmask_b32_e32 v21, v21, v22, vcc
	v_rsq_f32_e32 v20, v20
	v_rsq_f32_e32 v21, v21
	s_nop 0
	v_pk_mul_f32 v[22:23], v[20:21], s[2:3] op_sel_hi:[1,0]
	s_nop 0
	v_cndmask_b32_e32 v23, v21, v23, vcc
	v_cndmask_b32_e64 v22, v20, v22, s[4:5]
	flat_load_dwordx4 v[18:21], v[18:19] offset:16
	v_pk_mul_f32 v[10:11], v[10:11], v[22:23]
	v_mul_f32_e32 v2, v2, v22
	v_cvt_pk_bf16_f32 v10, v10, v11
	v_mul_f32_e32 v3, v3, v23
	v_cvt_pk_bf16_f32 v2, v2, v3
	s_waitcnt vmcnt(0) lgkmcnt(0)
	v_ffbh_u32_e32 v11, v21
	v_min_u32_e32 v11, 32, v11
	v_lshlrev_b64 v[20:21], v11, v[20:21]
	v_min_u32_e32 v20, 1, v20
	v_or_b32_e32 v20, v21, v20
	v_cvt_f32_u32_e32 v20, v20
	v_sub_u32_e32 v11, 32, v11
	v_ldexp_f32 v21, v20, v11
	v_ffbh_u32_e32 v11, v19
	v_min_u32_e32 v11, 32, v11
	v_lshlrev_b64 v[18:19], v11, v[18:19]
	v_min_u32_e32 v18, 1, v18
	v_or_b32_e32 v18, v19, v18
	v_cvt_f32_u32_e32 v18, v18
	v_sub_u32_e32 v11, 32, v11
	v_ldexp_f32 v20, v18, v11
	v_pk_fma_f32 v[18:19], v[20:21], s[0:1], v[136:137] op_sel_hi:[1,0,0]
	s_nop 0
	v_mul_f32_e32 v11, 0x4b800000, v18
	v_cmp_gt_f32_e64 s[4:5], s33, v18
	v_cmp_gt_f32_e32 vcc, s33, v19
	s_nop 0
	v_cndmask_b32_e64 v11, v18, v11, s[4:5]
	v_rsq_f32_e32 v18, v11
	v_mul_f32_e32 v11, 0x4b800000, v19
	v_cndmask_b32_e32 v11, v19, v11, vcc
	v_rsq_f32_e32 v19, v11
	s_nop 0
	v_pk_mul_f32 v[20:21], v[18:19], s[2:3] op_sel_hi:[1,0]
	s_nop 0
	v_cndmask_b32_e32 v19, v19, v21, vcc
	v_cndmask_b32_e64 v18, v18, v20, s[4:5]
	v_pk_mul_f32 v[12:13], v[12:13], v[18:19]
	v_mul_f32_e32 v4, v4, v18
	v_mul_f32_e32 v5, v5, v19
	v_cvt_pk_bf16_f32 v11, v12, v13
	v_cvt_pk_bf16_f32 v3, v4, v5
	ds_write_b64 v0, v[10:11]
	ds_write_b64 v0, v[2:3] offset:8448
	v_mul_f32_e32 v0, v14, v22
	v_mul_f32_e32 v2, v15, v23
	v_mul_f32_e32 v3, v16, v18
	v_mul_f32_e32 v4, v17, v19
	v_cvt_pk_bf16_f32 v2, v0, v2
	v_cvt_pk_bf16_f32 v3, v3, v4
	v_add_u32_e32 v0, v24, v118
	ds_write_b64 v0, v[2:3]
	v_mul_f32_e32 v0, v6, v22
	v_mul_f32_e32 v2, v7, v23
	v_mul_f32_e32 v3, v8, v18
	v_mul_f32_e32 v4, v9, v19
	v_cvt_pk_bf16_f32 v2, v0, v2
	v_cvt_pk_bf16_f32 v3, v3, v4
	v_add_u32_e32 v0, v24, v114
	ds_write_b64 v0, v[2:3]
	s_and_b32 s2, s10, 0x700
	v_mov_b32_e32 v0, 0x1020
	v_mad_i64_i32 v[2:3], s[0:1], s9, v0, v[132:133]
	s_lshl_b32 s90, s2, 1
	v_lshlrev_b32_e32 v0, 4, v140
	v_lshl_add_u64 v[2:3], v[2:3], 0, s[90:91]
	v_and_b32_e32 v0, 0x1f0, v0
	v_lshl_add_u64 v[2:3], v[2:3], 0, v[0:1]
	s_mov_b64 s[0:1], 0x16264820
	v_ashrrev_i32_e32 v8, 5, v140
	v_lshl_add_u64 v[2:3], v[2:3], 0, s[0:1]
	v_mad_u64_u32 v[4:5], s[0:1], v8, s72, v[0:1]
	s_waitcnt lgkmcnt(0)
	s_barrier
	ds_read_b128 v[4:7], v4
	s_movk_i32 s2, 0x1020
	v_mad_i64_i32 v[8:9], s[0:1], v8, s2, v[2:3]
	s_mov_b64 s[4:5], 0
	s_waitcnt lgkmcnt(0)
	flat_store_dwordx4 v[8:9], v[4:7] nt
	s_nop 1
	v_add_u32_e32 v4, 0x200, v140
	v_ashrrev_i32_e32 v8, 5, v4
	v_mad_u64_u32 v[4:5], s[0:1], v8, s72, v[0:1]
	ds_read_b128 v[4:7], v4
	v_mad_i64_i32 v[8:9], s[0:1], v8, s2, v[2:3]
	s_waitcnt lgkmcnt(0)
	flat_store_dwordx4 v[8:9], v[4:7] nt
	s_nop 1
	v_add_u32_e32 v4, 0x400, v140
	v_ashrrev_i32_e32 v8, 5, v4
	v_mad_u64_u32 v[4:5], s[0:1], v8, s72, v[0:1]
	ds_read_b128 v[4:7], v4
	v_mad_i64_i32 v[8:9], s[0:1], v8, s2, v[2:3]
	s_waitcnt lgkmcnt(0)
	flat_store_dwordx4 v[8:9], v[4:7] nt
	s_nop 1
	v_add_u32_e32 v4, 0x600, v140
	v_ashrrev_i32_e32 v8, 5, v4
	v_mad_u64_u32 v[4:5], s[0:1], v8, s72, v[0:1]
	ds_read_b128 v[4:7], v4
	v_mad_i64_i32 v[8:9], s[0:1], v8, s2, v[2:3]
	s_waitcnt lgkmcnt(0)
	flat_store_dwordx4 v[8:9], v[4:7] nt
	s_nop 1
	v_add_u32_e32 v4, 0x800, v140
	v_ashrrev_i32_e32 v8, 5, v4
	v_mad_u64_u32 v[4:5], s[0:1], v8, s72, v[0:1]
	ds_read_b128 v[4:7], v4
	v_mad_i64_i32 v[8:9], s[0:1], v8, s2, v[2:3]
	s_waitcnt lgkmcnt(0)
	flat_store_dwordx4 v[8:9], v[4:7] nt
	s_nop 1
	v_add_u32_e32 v4, 0xa00, v140
	v_ashrrev_i32_e32 v8, 5, v4
	v_mad_u64_u32 v[4:5], s[0:1], v8, s72, v[0:1]
	ds_read_b128 v[4:7], v4
	v_mad_i64_i32 v[8:9], s[0:1], v8, s2, v[2:3]
	s_waitcnt lgkmcnt(0)
	flat_store_dwordx4 v[8:9], v[4:7] nt
	s_nop 1
	v_add_u32_e32 v4, 0xc00, v140
	v_ashrrev_i32_e32 v8, 5, v4
	v_mad_u64_u32 v[4:5], s[0:1], v8, s72, v[0:1]
	ds_read_b128 v[4:7], v4
	v_mad_i64_i32 v[8:9], s[0:1], v8, s2, v[2:3]
	s_waitcnt lgkmcnt(0)
	flat_store_dwordx4 v[8:9], v[4:7] nt
	s_nop 1
	v_add_u32_e32 v4, 0xe00, v140
	v_ashrrev_i32_e32 v8, 5, v4
	v_mad_u64_u32 v[4:5], s[0:1], v8, s72, v[0:1]
	ds_read_b128 v[4:7], v4
	v_mad_i64_i32 v[8:9], s[0:1], v8, s2, v[2:3]
	s_waitcnt lgkmcnt(0)
	flat_store_dwordx4 v[8:9], v[4:7] nt
	s_nop 1
	v_add_u32_e32 v4, 0x1000, v140
	v_ashrrev_i32_e32 v8, 5, v4
	v_mad_u64_u32 v[4:5], s[0:1], v8, s72, v[0:1]
	ds_read_b128 v[4:7], v4
	v_mad_i64_i32 v[8:9], s[0:1], v8, s2, v[2:3]
	s_waitcnt lgkmcnt(0)
	flat_store_dwordx4 v[8:9], v[4:7] nt
	s_nop 1
	v_add_u32_e32 v4, 0x1200, v140
	v_ashrrev_i32_e32 v8, 5, v4
	v_mad_u64_u32 v[4:5], s[0:1], v8, s72, v[0:1]
	ds_read_b128 v[4:7], v4
	v_mad_i64_i32 v[8:9], s[0:1], v8, s2, v[2:3]
	s_waitcnt lgkmcnt(0)
	flat_store_dwordx4 v[8:9], v[4:7] nt
	s_nop 1
	v_add_u32_e32 v4, 0x1400, v140
	v_ashrrev_i32_e32 v8, 5, v4
	v_mad_u64_u32 v[4:5], s[0:1], v8, s72, v[0:1]
	ds_read_b128 v[4:7], v4
	v_mad_i64_i32 v[8:9], s[0:1], v8, s2, v[2:3]
	s_waitcnt lgkmcnt(0)
	flat_store_dwordx4 v[8:9], v[4:7] nt
	s_nop 1
	v_add_u32_e32 v4, 0x1600, v140
	v_ashrrev_i32_e32 v8, 5, v4
	v_mad_u64_u32 v[4:5], s[0:1], v8, s72, v[0:1]
	ds_read_b128 v[4:7], v4
	v_mad_i64_i32 v[8:9], s[0:1], v8, s2, v[2:3]
	s_waitcnt lgkmcnt(0)
	flat_store_dwordx4 v[8:9], v[4:7] nt
	s_nop 1
	v_add_u32_e32 v4, 0x1800, v140
	v_ashrrev_i32_e32 v8, 5, v4
	v_mad_u64_u32 v[4:5], s[0:1], v8, s72, v[0:1]
	ds_read_b128 v[4:7], v4
	v_mad_i64_i32 v[8:9], s[0:1], v8, s2, v[2:3]
	s_waitcnt lgkmcnt(0)
	flat_store_dwordx4 v[8:9], v[4:7] nt
	s_nop 1
	v_add_u32_e32 v4, 0x1a00, v140
	v_ashrrev_i32_e32 v8, 5, v4
	v_mad_u64_u32 v[4:5], s[0:1], v8, s72, v[0:1]
	ds_read_b128 v[4:7], v4
	v_mad_i64_i32 v[8:9], s[0:1], v8, s2, v[2:3]
	s_waitcnt lgkmcnt(0)
	flat_store_dwordx4 v[8:9], v[4:7] nt
	s_nop 1
	v_add_u32_e32 v4, 0x1c00, v140
	v_ashrrev_i32_e32 v4, 5, v4
	v_mad_u64_u32 v[6:7], s[0:1], v4, s72, v[0:1]
	ds_read_b128 v[6:9], v6
	v_mad_i64_i32 v[4:5], s[0:1], v4, s2, v[2:3]
	s_waitcnt lgkmcnt(0)
	flat_store_dwordx4 v[4:5], v[6:9] nt
	v_add_u32_e32 v4, 0x1e00, v140
	s_nop 0
	v_ashrrev_i32_e32 v8, 5, v4
	v_mad_u64_u32 v[4:5], s[0:1], v8, s72, v[0:1]
	ds_read_b128 v[4:7], v4
	v_mad_i64_i32 v[2:3], s[0:1], v8, s2, v[2:3]
	s_waitcnt lgkmcnt(0)
	flat_store_dwordx4 v[2:3], v[4:7] nt
	s_waitcnt lgkmcnt(0)
	s_barrier

.LBB0_112:
	v_mov_b32_e32 v132, v204
	s_waitcnt vmcnt(0)
	v_and_b32_e32 v0, 15, v132
	v_ashrrev_i32_e32 v133, 2, v132
	v_and_b32_e32 v136, 0xffffffc0, v133
	v_or_b32_e32 v133, s10, v0
	v_add_u32_e32 v138, v133, v136
	v_ashrrev_i32_e32 v139, 31, v138
	v_lshl_add_u64 v[138:139], v[138:139], 3, v[130:131]
	s_barrier
	flat_load_dwordx2 v[138:139], v[138:139]
	v_mov_b32_e32 v140, 0x358637bd
	s_mov_b32 s9, s91
	s_mov_b64 s[0:1], 0xe253800
	v_mov_b32_e32 v253, 0x358637bd
	s_mov_b64 s[4:5], 0
	s_waitcnt vmcnt(0) lgkmcnt(0)
	v_ffbh_u32_e32 v137, v139
	v_min_u32_e32 v137, 32, v137
	v_lshlrev_b64 v[138:139], v137, v[138:139]
	v_min_u32_e32 v138, 1, v138
	v_or_b32_e32 v138, v139, v138
	v_cvt_f32_u32_e32 v138, v138
	v_sub_u32_e32 v137, 32, v137
	v_ldexp_f32 v137, v138, v137
	v_fmamk_f32 v137, v137, 0x30000000, v140
	v_cmp_gt_f32_e32 vcc, s33, v137
	v_mul_f32_e32 v138, 0x4b800000, v137
	s_nop 0
	v_cndmask_b32_e32 v137, v137, v138, vcc
	v_rsq_f32_e32 v137, v137
	s_nop 0
	v_mul_f32_e32 v138, 0x45800000, v137
	v_cndmask_b32_e32 v137, v137, v138, vcc
	v_mul_f32_e32 v126, v126, v137
	v_mul_f32_e32 v127, v127, v137
	v_or_b32_e32 v138, v136, v0
	v_mul_f32_e32 v139, v128, v137
	v_cvt_pk_bf16_f32 v128, v126, v127
	v_lshrrev_b32_e32 v126, 1, v132
	v_mul_lo_u32 v138, v138, s72
	v_mul_f32_e32 v129, v129, v137
	v_and_b32_e32 v126, 24, v126
	v_and_b32_e32 v127, 0xc0, v132
	v_mul_f32_e32 v114, v114, v137
	v_mul_f32_e32 v115, v115, v137
	v_mul_f32_e32 v116, v116, v137
	v_mul_f32_e32 v117, v117, v137
	v_cvt_pk_bf16_f32 v129, v139, v129
	v_add3_u32 v138, v138, v127, v126
	v_cvt_pk_bf16_f32 v114, v114, v115
	v_cvt_pk_bf16_f32 v115, v116, v117
	ds_write2_b64 v138, v[128:129], v[114:115] offset1:4
	v_mul_f32_e32 v114, v122, v137
	v_mul_f32_e32 v115, v123, v137
	v_mul_f32_e32 v116, v124, v137
	v_mul_f32_e32 v117, v125, v137
	v_cvt_pk_bf16_f32 v114, v114, v115
	v_cvt_pk_bf16_f32 v115, v116, v117
	v_mul_f32_e32 v116, v118, v137
	v_mul_f32_e32 v117, v119, v137
	v_mul_f32_e32 v118, v120, v137
	v_mul_f32_e32 v119, v121, v137
	v_cvt_pk_bf16_f32 v116, v116, v117
	v_cvt_pk_bf16_f32 v117, v118, v119
	ds_write2_b64 v138, v[114:115], v[116:117] offset0:32 offset1:36
	v_or_b32_e32 v116, 16, v136
	v_add_u32_e32 v114, v116, v133
	v_ashrrev_i32_e32 v115, 31, v114
	v_lshl_add_u64 v[114:115], v[114:115], 3, v[130:131]
	flat_load_dwordx2 v[114:115], v[114:115]
	s_waitcnt vmcnt(0) lgkmcnt(0)
	v_ffbh_u32_e32 v117, v115
	v_min_u32_e32 v117, 32, v117
	v_lshlrev_b64 v[114:115], v117, v[114:115]
	v_min_u32_e32 v114, 1, v114
	v_or_b32_e32 v114, v115, v114
	v_cvt_f32_u32_e32 v114, v114
	v_sub_u32_e32 v115, 32, v117
	v_ldexp_f32 v114, v114, v115
	v_fmamk_f32 v114, v114, 0x30000000, v140
	v_cmp_gt_f32_e32 vcc, s33, v114
	v_mul_f32_e32 v115, 0x4b800000, v114
	s_nop 0
	v_cndmask_b32_e32 v114, v114, v115, vcc
	v_rsq_f32_e32 v114, v114
	s_nop 0
	v_mul_f32_e32 v115, 0x45800000, v114
	v_cndmask_b32_e32 v114, v114, v115, vcc
	v_or_b32_e32 v115, v116, v0
	v_mul_lo_u32 v115, v115, s72
	v_mul_f32_e32 v102, v102, v114
	v_mul_f32_e32 v103, v103, v114
	v_mul_f32_e32 v104, v104, v114
	v_mul_f32_e32 v105, v105, v114
	v_mul_f32_e32 v98, v98, v114
	v_mul_f32_e32 v99, v99, v114
	v_mul_f32_e32 v100, v100, v114
	v_mul_f32_e32 v101, v101, v114
	v_cvt_pk_bf16_f32 v102, v102, v103
	v_cvt_pk_bf16_f32 v103, v104, v105
	v_add3_u32 v104, v115, v127, v126
	v_cvt_pk_bf16_f32 v98, v98, v99
	v_cvt_pk_bf16_f32 v99, v100, v101
	ds_write2_b64 v104, v[102:103], v[98:99] offset1:4
	v_mul_f32_e32 v98, v110, v114
	v_mul_f32_e32 v99, v111, v114
	v_mul_f32_e32 v100, v112, v114
	v_mul_f32_e32 v101, v113, v114
	v_cvt_pk_bf16_f32 v98, v98, v99
	v_cvt_pk_bf16_f32 v99, v100, v101
	v_mul_f32_e32 v100, v106, v114
	v_mul_f32_e32 v101, v107, v114
	v_mul_f32_e32 v102, v108, v114
	v_mul_f32_e32 v103, v109, v114
	v_cvt_pk_bf16_f32 v100, v100, v101
	v_cvt_pk_bf16_f32 v101, v102, v103
	ds_write2_b64 v104, v[98:99], v[100:101] offset0:32 offset1:36
	v_or_b32_e32 v100, 32, v136
	v_add_u32_e32 v98, v100, v133
	v_ashrrev_i32_e32 v99, 31, v98
	v_lshl_add_u64 v[98:99], v[98:99], 3, v[130:131]
	flat_load_dwordx2 v[98:99], v[98:99]
	s_waitcnt vmcnt(0) lgkmcnt(0)
	v_ffbh_u32_e32 v101, v99
	v_min_u32_e32 v101, 32, v101
	v_lshlrev_b64 v[98:99], v101, v[98:99]
	v_min_u32_e32 v98, 1, v98
	v_or_b32_e32 v98, v99, v98
	v_cvt_f32_u32_e32 v98, v98
	v_sub_u32_e32 v99, 32, v101
	v_ldexp_f32 v98, v98, v99
	v_fmamk_f32 v98, v98, 0x30000000, v140
	v_cmp_gt_f32_e32 vcc, s33, v98
	v_mul_f32_e32 v99, 0x4b800000, v98
	s_nop 0
	v_cndmask_b32_e32 v98, v98, v99, vcc
	v_rsq_f32_e32 v98, v98
	s_nop 0
	v_mul_f32_e32 v99, 0x45800000, v98
	v_cndmask_b32_e32 v98, v98, v99, vcc
	v_or_b32_e32 v99, v100, v0
	v_mul_lo_u32 v99, v99, s72
	v_mul_f32_e32 v86, v86, v98
	v_mul_f32_e32 v87, v87, v98
	v_mul_f32_e32 v88, v88, v98
	v_mul_f32_e32 v89, v89, v98
	v_mul_f32_e32 v82, v82, v98
	v_mul_f32_e32 v83, v83, v98
	v_mul_f32_e32 v84, v84, v98
	v_mul_f32_e32 v85, v85, v98
	v_cvt_pk_bf16_f32 v86, v86, v87
	v_cvt_pk_bf16_f32 v87, v88, v89
	v_add3_u32 v88, v99, v127, v126
	v_cvt_pk_bf16_f32 v82, v82, v83
	v_cvt_pk_bf16_f32 v83, v84, v85
	ds_write2_b64 v88, v[86:87], v[82:83] offset1:4
	v_mul_f32_e32 v82, v94, v98
	v_mul_f32_e32 v83, v95, v98
	v_mul_f32_e32 v84, v96, v98
	v_mul_f32_e32 v85, v97, v98
	v_cvt_pk_bf16_f32 v82, v82, v83
	v_cvt_pk_bf16_f32 v83, v84, v85
	v_mul_f32_e32 v84, v90, v98
	v_mul_f32_e32 v85, v91, v98
	v_mul_f32_e32 v86, v92, v98
	v_mul_f32_e32 v87, v93, v98
	v_cvt_pk_bf16_f32 v84, v84, v85
	v_cvt_pk_bf16_f32 v85, v86, v87
	ds_write2_b64 v88, v[82:83], v[84:85] offset0:32 offset1:36
	v_or_b32_e32 v84, 48, v136
	v_add_u32_e32 v82, v84, v133
	v_ashrrev_i32_e32 v83, 31, v82
	v_lshl_add_u64 v[82:83], v[82:83], 3, v[130:131]
	flat_load_dwordx2 v[82:83], v[82:83]
	s_waitcnt vmcnt(0) lgkmcnt(0)
	v_ffbh_u32_e32 v85, v83
	v_min_u32_e32 v85, 32, v85
	v_lshlrev_b64 v[82:83], v85, v[82:83]
	v_min_u32_e32 v82, 1, v82
	v_or_b32_e32 v82, v83, v82
	v_cvt_f32_u32_e32 v82, v82
	v_sub_u32_e32 v83, 32, v85
	v_ldexp_f32 v82, v82, v83
	v_fmamk_f32 v82, v82, 0x30000000, v140
	v_cmp_gt_f32_e32 vcc, s33, v82
	v_mul_f32_e32 v83, 0x4b800000, v82
	s_nop 0
	v_cndmask_b32_e32 v82, v82, v83, vcc
	v_rsq_f32_e32 v82, v82
	s_nop 0
	v_mul_f32_e32 v83, 0x45800000, v82
	v_cndmask_b32_e32 v82, v82, v83, vcc
	v_or_b32_e32 v83, v84, v0
	v_mul_lo_u32 v83, v83, s72
	v_mul_f32_e32 v70, v70, v82
	v_mul_f32_e32 v71, v71, v82
	v_mul_f32_e32 v72, v72, v82
	v_mul_f32_e32 v73, v73, v82
	v_mul_f32_e32 v66, v66, v82
	v_mul_f32_e32 v67, v67, v82
	v_mul_f32_e32 v68, v68, v82
	v_mul_f32_e32 v69, v69, v82
	v_cvt_pk_bf16_f32 v70, v70, v71
	v_cvt_pk_bf16_f32 v71, v72, v73
	v_add3_u32 v72, v83, v127, v126
	v_cvt_pk_bf16_f32 v66, v66, v67
	v_cvt_pk_bf16_f32 v67, v68, v69
	ds_write2_b64 v72, v[70:71], v[66:67] offset1:4
	v_mul_f32_e32 v66, v78, v82
	v_mul_f32_e32 v67, v79, v82
	v_mul_f32_e32 v68, v80, v82
	v_mul_f32_e32 v69, v81, v82
	v_cvt_pk_bf16_f32 v66, v66, v67
	v_cvt_pk_bf16_f32 v67, v68, v69
	v_mul_f32_e32 v68, v74, v82
	v_mul_f32_e32 v69, v75, v82
	v_mul_f32_e32 v70, v76, v82
	v_mul_f32_e32 v71, v77, v82
	v_cvt_pk_bf16_f32 v68, v68, v69
	v_cvt_pk_bf16_f32 v69, v70, v71
	ds_write2_b64 v72, v[66:67], v[68:69] offset0:32 offset1:36
	v_add_u32_e32 v68, 0x80, v136
	v_add_u32_e32 v66, v68, v133
	v_ashrrev_i32_e32 v67, 31, v66
	v_lshl_add_u64 v[66:67], v[66:67], 3, v[130:131]
	flat_load_dwordx2 v[66:67], v[66:67]
	s_waitcnt vmcnt(0) lgkmcnt(0)
	v_ffbh_u32_e32 v69, v67
	v_min_u32_e32 v69, 32, v69
	v_lshlrev_b64 v[66:67], v69, v[66:67]
	v_min_u32_e32 v66, 1, v66
	v_or_b32_e32 v66, v67, v66
	v_cvt_f32_u32_e32 v66, v66
	v_sub_u32_e32 v67, 32, v69
	v_ldexp_f32 v66, v66, v67
	v_fmamk_f32 v66, v66, 0x30000000, v140
	v_cmp_gt_f32_e32 vcc, s33, v66
	v_mul_f32_e32 v67, 0x4b800000, v66
	s_nop 0
	v_cndmask_b32_e32 v66, v66, v67, vcc
	v_rsq_f32_e32 v66, v66
	s_nop 0
	v_mul_f32_e32 v67, 0x45800000, v66
	v_cndmask_b32_e32 v66, v66, v67, vcc
	v_or_b32_e32 v67, v68, v0
	v_mul_lo_u32 v67, v67, s72
	v_mul_f32_e32 v54, v54, v66
	v_mul_f32_e32 v55, v55, v66
	v_mul_f32_e32 v56, v56, v66
	v_mul_f32_e32 v57, v57, v66
	v_mul_f32_e32 v50, v50, v66
	v_mul_f32_e32 v51, v51, v66
	v_mul_f32_e32 v52, v52, v66
	v_mul_f32_e32 v53, v53, v66
	v_cvt_pk_bf16_f32 v54, v54, v55
	v_cvt_pk_bf16_f32 v55, v56, v57
	v_add3_u32 v56, v67, v127, v126
	v_cvt_pk_bf16_f32 v50, v50, v51
	v_cvt_pk_bf16_f32 v51, v52, v53
	ds_write2_b64 v56, v[54:55], v[50:51] offset1:4
	v_mul_f32_e32 v50, v62, v66
	v_mul_f32_e32 v51, v63, v66
	v_mul_f32_e32 v52, v64, v66
	v_mul_f32_e32 v53, v65, v66
	v_cvt_pk_bf16_f32 v50, v50, v51
	v_cvt_pk_bf16_f32 v51, v52, v53
	v_mul_f32_e32 v52, v58, v66
	v_mul_f32_e32 v53, v59, v66
	v_mul_f32_e32 v54, v60, v66
	v_mul_f32_e32 v55, v61, v66
	v_cvt_pk_bf16_f32 v52, v52, v53
	v_cvt_pk_bf16_f32 v53, v54, v55
	ds_write2_b64 v56, v[50:51], v[52:53] offset0:32 offset1:36
	v_add_u32_e32 v52, 0x90, v136
	v_add_u32_e32 v50, v52, v133
	v_ashrrev_i32_e32 v51, 31, v50
	v_lshl_add_u64 v[50:51], v[50:51], 3, v[130:131]
	flat_load_dwordx2 v[50:51], v[50:51]
	s_waitcnt vmcnt(0) lgkmcnt(0)
	v_ffbh_u32_e32 v53, v51
	v_min_u32_e32 v53, 32, v53
	v_lshlrev_b64 v[50:51], v53, v[50:51]
	v_min_u32_e32 v50, 1, v50
	v_or_b32_e32 v50, v51, v50
	v_cvt_f32_u32_e32 v50, v50
	v_sub_u32_e32 v51, 32, v53
	v_ldexp_f32 v50, v50, v51
	v_fmamk_f32 v50, v50, 0x30000000, v140
	v_cmp_gt_f32_e32 vcc, s33, v50
	v_mul_f32_e32 v51, 0x4b800000, v50
	s_nop 0
	v_cndmask_b32_e32 v50, v50, v51, vcc
	v_rsq_f32_e32 v50, v50
	s_nop 0
	v_mul_f32_e32 v51, 0x45800000, v50
	v_cndmask_b32_e32 v50, v50, v51, vcc
	v_or_b32_e32 v51, v52, v0
	v_mul_lo_u32 v51, v51, s72
	v_mul_f32_e32 v38, v38, v50
	v_mul_f32_e32 v39, v39, v50
	v_mul_f32_e32 v40, v40, v50
	v_mul_f32_e32 v41, v41, v50
	v_mul_f32_e32 v34, v34, v50
	v_mul_f32_e32 v35, v35, v50
	v_mul_f32_e32 v36, v36, v50
	v_mul_f32_e32 v37, v37, v50
	v_cvt_pk_bf16_f32 v38, v38, v39
	v_cvt_pk_bf16_f32 v39, v40, v41
	v_add3_u32 v40, v51, v127, v126
	v_cvt_pk_bf16_f32 v34, v34, v35
	v_cvt_pk_bf16_f32 v35, v36, v37
	ds_write2_b64 v40, v[38:39], v[34:35] offset1:4
	v_mul_f32_e32 v34, v46, v50
	v_mul_f32_e32 v35, v47, v50
	v_mul_f32_e32 v36, v48, v50
	v_mul_f32_e32 v37, v49, v50
	v_cvt_pk_bf16_f32 v34, v34, v35
	v_cvt_pk_bf16_f32 v35, v36, v37
	v_mul_f32_e32 v36, v42, v50
	v_mul_f32_e32 v37, v43, v50
	v_mul_f32_e32 v38, v44, v50
	v_mul_f32_e32 v39, v45, v50
	v_cvt_pk_bf16_f32 v36, v36, v37
	v_cvt_pk_bf16_f32 v37, v38, v39
	ds_write2_b64 v40, v[34:35], v[36:37] offset0:32 offset1:36
	v_add_u32_e32 v36, 0xa0, v136
	v_add_u32_e32 v34, v36, v133
	v_ashrrev_i32_e32 v35, 31, v34
	v_lshl_add_u64 v[34:35], v[34:35], 3, v[130:131]
	flat_load_dwordx2 v[34:35], v[34:35]
	s_waitcnt vmcnt(0) lgkmcnt(0)
	v_ffbh_u32_e32 v37, v35
	v_min_u32_e32 v37, 32, v37
	v_lshlrev_b64 v[34:35], v37, v[34:35]
	v_min_u32_e32 v34, 1, v34
	v_or_b32_e32 v34, v35, v34
	v_cvt_f32_u32_e32 v34, v34
	v_sub_u32_e32 v35, 32, v37
	v_ldexp_f32 v34, v34, v35
	v_fmamk_f32 v34, v34, 0x30000000, v140
	v_cmp_gt_f32_e32 vcc, s33, v34
	v_mul_f32_e32 v35, 0x4b800000, v34
	s_nop 0
	v_cndmask_b32_e32 v34, v34, v35, vcc
	v_rsq_f32_e32 v34, v34
	s_nop 0
	v_mul_f32_e32 v35, 0x45800000, v34
	v_cndmask_b32_e32 v34, v34, v35, vcc
	v_or_b32_e32 v35, v36, v0
	v_mul_lo_u32 v35, v35, s72
	v_mul_f32_e32 v22, v22, v34
	v_mul_f32_e32 v23, v23, v34
	v_mul_f32_e32 v24, v24, v34
	v_mul_f32_e32 v25, v25, v34
	v_mul_f32_e32 v18, v18, v34
	v_mul_f32_e32 v19, v19, v34
	v_mul_f32_e32 v20, v20, v34
	v_mul_f32_e32 v21, v21, v34
	v_cvt_pk_bf16_f32 v22, v22, v23
	v_cvt_pk_bf16_f32 v23, v24, v25
	v_add3_u32 v24, v35, v127, v126
	v_cvt_pk_bf16_f32 v18, v18, v19
	v_cvt_pk_bf16_f32 v19, v20, v21
	ds_write2_b64 v24, v[22:23], v[18:19] offset1:4
	v_mul_f32_e32 v18, v30, v34
	v_mul_f32_e32 v19, v31, v34
	v_mul_f32_e32 v20, v32, v34
	v_mul_f32_e32 v21, v33, v34
	v_cvt_pk_bf16_f32 v18, v18, v19
	v_cvt_pk_bf16_f32 v19, v20, v21
	v_mul_f32_e32 v20, v26, v34
	v_mul_f32_e32 v21, v27, v34
	v_mul_f32_e32 v22, v28, v34
	v_mul_f32_e32 v23, v29, v34
	v_cvt_pk_bf16_f32 v20, v20, v21
	v_cvt_pk_bf16_f32 v21, v22, v23
	ds_write2_b64 v24, v[18:19], v[20:21] offset0:32 offset1:36
	v_add_u32_e32 v20, 0xb0, v136
	v_add_u32_e32 v18, v20, v133
	v_ashrrev_i32_e32 v19, 31, v18
	v_lshl_add_u64 v[18:19], v[18:19], 3, v[130:131]
	flat_load_dwordx2 v[18:19], v[18:19]
	v_or_b32_e32 v0, v20, v0
	v_mul_lo_u32 v0, v0, s72
	v_add3_u32 v0, v0, v127, v126
	s_waitcnt vmcnt(0) lgkmcnt(0)
	v_ffbh_u32_e32 v21, v19
	v_min_u32_e32 v21, 32, v21
	v_lshlrev_b64 v[18:19], v21, v[18:19]
	v_min_u32_e32 v18, 1, v18
	v_or_b32_e32 v18, v19, v18
	v_cvt_f32_u32_e32 v18, v18
	v_sub_u32_e32 v19, 32, v21
	v_ldexp_f32 v18, v18, v19
	v_fmamk_f32 v18, v18, 0x30000000, v140
	v_cmp_gt_f32_e32 vcc, s33, v18
	v_mul_f32_e32 v19, 0x4b800000, v18
	s_nop 0
	v_cndmask_b32_e32 v18, v18, v19, vcc
	v_rsq_f32_e32 v18, v18
	s_nop 0
	v_mul_f32_e32 v19, 0x45800000, v18
	v_cndmask_b32_e32 v18, v18, v19, vcc
	v_mul_f32_e32 v6, v6, v18
	v_mul_f32_e32 v7, v7, v18
	v_mul_f32_e32 v8, v8, v18
	v_mul_f32_e32 v9, v9, v18
	v_mul_f32_e32 v2, v2, v18
	v_mul_f32_e32 v3, v3, v18
	v_mul_f32_e32 v4, v4, v18
	v_mul_f32_e32 v5, v5, v18
	v_cvt_pk_bf16_f32 v6, v6, v7
	v_cvt_pk_bf16_f32 v7, v8, v9
	v_cvt_pk_bf16_f32 v2, v2, v3
	v_cvt_pk_bf16_f32 v3, v4, v5
	ds_write2_b64 v0, v[6:7], v[2:3] offset1:4
	v_mul_f32_e32 v2, v14, v18
	v_mul_f32_e32 v3, v15, v18
	v_mul_f32_e32 v4, v16, v18
	v_mul_f32_e32 v5, v17, v18
	v_cvt_pk_bf16_f32 v2, v2, v3
	v_cvt_pk_bf16_f32 v3, v4, v5
	v_mul_f32_e32 v4, v10, v18
	v_mul_f32_e32 v5, v11, v18
	v_mul_f32_e32 v6, v12, v18
	v_mul_f32_e32 v7, v13, v18
	v_cvt_pk_bf16_f32 v4, v4, v5
	v_cvt_pk_bf16_f32 v5, v6, v7
	ds_write2_b64 v0, v[2:3], v[4:5] offset0:32 offset1:36
	v_lshlrev_b32_e32 v0, 4, v132
	v_lshl_add_u64 v[2:3], s[8:9], 1, v[134:135]
	v_and_b32_e32 v0, 0x1f0, v0
	v_lshl_add_u64 v[2:3], v[2:3], 0, v[0:1]
	v_ashrrev_i32_e32 v8, 5, v132
	v_lshl_add_u64 v[2:3], v[2:3], 0, s[0:1]
	v_mad_u64_u32 v[4:5], s[0:1], v8, s72, v[0:1]
	s_waitcnt lgkmcnt(0)
	s_barrier
	ds_read_b128 v[4:7], v4
	v_ashrrev_i32_e32 v9, 31, v8
	v_lshlrev_b64 v[8:9], 12, v[8:9]
	v_lshl_add_u64 v[8:9], v[2:3], 0, v[8:9]
	s_waitcnt lgkmcnt(0)
	flat_store_dwordx4 v[8:9], v[4:7] nt
	s_nop 1
	v_add_u32_e32 v4, 0x200, v132
	v_ashrrev_i32_e32 v8, 5, v4
	v_mad_u64_u32 v[4:5], s[0:1], v8, s72, v[0:1]
	ds_read_b128 v[4:7], v4
	v_ashrrev_i32_e32 v9, 31, v8
	v_lshlrev_b64 v[8:9], 12, v[8:9]
	v_lshl_add_u64 v[8:9], v[2:3], 0, v[8:9]
	s_waitcnt lgkmcnt(0)
	flat_store_dwordx4 v[8:9], v[4:7] nt
	s_nop 1
	v_add_u32_e32 v4, 0x400, v132
	v_ashrrev_i32_e32 v8, 5, v4
	v_mad_u64_u32 v[4:5], s[0:1], v8, s72, v[0:1]
	ds_read_b128 v[4:7], v4
	v_ashrrev_i32_e32 v9, 31, v8
	v_lshlrev_b64 v[8:9], 12, v[8:9]
	v_lshl_add_u64 v[8:9], v[2:3], 0, v[8:9]
	s_waitcnt lgkmcnt(0)
	flat_store_dwordx4 v[8:9], v[4:7] nt
	s_nop 1
	v_add_u32_e32 v4, 0x600, v132
	v_ashrrev_i32_e32 v8, 5, v4
	v_mad_u64_u32 v[4:5], s[0:1], v8, s72, v[0:1]
	ds_read_b128 v[4:7], v4
	v_ashrrev_i32_e32 v9, 31, v8
	v_lshlrev_b64 v[8:9], 12, v[8:9]
	v_lshl_add_u64 v[8:9], v[2:3], 0, v[8:9]
	s_waitcnt lgkmcnt(0)
	flat_store_dwordx4 v[8:9], v[4:7] nt
	s_nop 1
	v_add_u32_e32 v4, 0x800, v132
	v_ashrrev_i32_e32 v8, 5, v4
	v_mad_u64_u32 v[4:5], s[0:1], v8, s72, v[0:1]
	ds_read_b128 v[4:7], v4
	v_ashrrev_i32_e32 v9, 31, v8
	v_lshlrev_b64 v[8:9], 12, v[8:9]
	v_lshl_add_u64 v[8:9], v[2:3], 0, v[8:9]
	s_waitcnt lgkmcnt(0)
	flat_store_dwordx4 v[8:9], v[4:7] nt
	s_nop 1
	v_add_u32_e32 v4, 0xa00, v132
	v_ashrrev_i32_e32 v8, 5, v4
	v_mad_u64_u32 v[4:5], s[0:1], v8, s72, v[0:1]
	ds_read_b128 v[4:7], v4
	v_ashrrev_i32_e32 v9, 31, v8
	v_lshlrev_b64 v[8:9], 12, v[8:9]
	v_lshl_add_u64 v[8:9], v[2:3], 0, v[8:9]
	s_waitcnt lgkmcnt(0)
	flat_store_dwordx4 v[8:9], v[4:7] nt
	s_nop 1
	v_add_u32_e32 v4, 0xc00, v132
	v_ashrrev_i32_e32 v8, 5, v4
	v_mad_u64_u32 v[4:5], s[0:1], v8, s72, v[0:1]
	ds_read_b128 v[4:7], v4
	v_ashrrev_i32_e32 v9, 31, v8
	v_lshlrev_b64 v[8:9], 12, v[8:9]
	v_lshl_add_u64 v[8:9], v[2:3], 0, v[8:9]
	s_waitcnt lgkmcnt(0)
	flat_store_dwordx4 v[8:9], v[4:7] nt
	s_nop 1
	v_add_u32_e32 v4, 0xe00, v132
	v_ashrrev_i32_e32 v8, 5, v4
	v_mad_u64_u32 v[4:5], s[0:1], v8, s72, v[0:1]
	ds_read_b128 v[4:7], v4
	v_ashrrev_i32_e32 v9, 31, v8
	v_lshlrev_b64 v[8:9], 12, v[8:9]
	v_lshl_add_u64 v[8:9], v[2:3], 0, v[8:9]
	s_waitcnt lgkmcnt(0)
	flat_store_dwordx4 v[8:9], v[4:7] nt
	s_nop 1
	v_add_u32_e32 v4, 0x1000, v132
	v_ashrrev_i32_e32 v8, 5, v4
	v_mad_u64_u32 v[4:5], s[0:1], v8, s72, v[0:1]
	ds_read_b128 v[4:7], v4
	v_ashrrev_i32_e32 v9, 31, v8
	v_lshlrev_b64 v[8:9], 12, v[8:9]
	v_lshl_add_u64 v[8:9], v[2:3], 0, v[8:9]
	s_waitcnt lgkmcnt(0)
	flat_store_dwordx4 v[8:9], v[4:7] nt
	s_nop 1
	v_add_u32_e32 v4, 0x1200, v132
	v_ashrrev_i32_e32 v8, 5, v4
	v_mad_u64_u32 v[4:5], s[0:1], v8, s72, v[0:1]
	ds_read_b128 v[4:7], v4
	v_ashrrev_i32_e32 v9, 31, v8
	v_lshlrev_b64 v[8:9], 12, v[8:9]
	v_lshl_add_u64 v[8:9], v[2:3], 0, v[8:9]
	s_waitcnt lgkmcnt(0)
	flat_store_dwordx4 v[8:9], v[4:7] nt
	s_nop 1
	v_add_u32_e32 v4, 0x1400, v132
	v_ashrrev_i32_e32 v8, 5, v4
	v_mad_u64_u32 v[4:5], s[0:1], v8, s72, v[0:1]
	ds_read_b128 v[4:7], v4
	v_ashrrev_i32_e32 v9, 31, v8
	v_lshlrev_b64 v[8:9], 12, v[8:9]
	v_lshl_add_u64 v[8:9], v[2:3], 0, v[8:9]
	s_waitcnt lgkmcnt(0)
	flat_store_dwordx4 v[8:9], v[4:7] nt
	s_nop 1
	v_add_u32_e32 v4, 0x1600, v132
	v_ashrrev_i32_e32 v8, 5, v4
	v_mad_u64_u32 v[4:5], s[0:1], v8, s72, v[0:1]
	ds_read_b128 v[4:7], v4
	v_ashrrev_i32_e32 v9, 31, v8
	v_lshlrev_b64 v[8:9], 12, v[8:9]
	v_lshl_add_u64 v[8:9], v[2:3], 0, v[8:9]
	s_waitcnt lgkmcnt(0)
	flat_store_dwordx4 v[8:9], v[4:7] nt
	s_nop 1
	v_add_u32_e32 v4, 0x1800, v132
	v_ashrrev_i32_e32 v8, 5, v4
	v_mad_u64_u32 v[4:5], s[0:1], v8, s72, v[0:1]
	ds_read_b128 v[4:7], v4
	v_ashrrev_i32_e32 v9, 31, v8
	v_lshlrev_b64 v[8:9], 12, v[8:9]
	v_lshl_add_u64 v[8:9], v[2:3], 0, v[8:9]
	s_waitcnt lgkmcnt(0)
	flat_store_dwordx4 v[8:9], v[4:7] nt
	s_nop 1
	v_add_u32_e32 v4, 0x1a00, v132
	v_ashrrev_i32_e32 v8, 5, v4
	v_mad_u64_u32 v[4:5], s[0:1], v8, s72, v[0:1]
	ds_read_b128 v[4:7], v4
	v_ashrrev_i32_e32 v9, 31, v8
	v_lshlrev_b64 v[8:9], 12, v[8:9]
	v_lshl_add_u64 v[8:9], v[2:3], 0, v[8:9]
	s_waitcnt lgkmcnt(0)
	flat_store_dwordx4 v[8:9], v[4:7] nt
	s_nop 1
	v_add_u32_e32 v4, 0x1c00, v132
	v_ashrrev_i32_e32 v8, 5, v4
	v_mad_u64_u32 v[4:5], s[0:1], v8, s72, v[0:1]
	ds_read_b128 v[4:7], v4
	v_ashrrev_i32_e32 v9, 31, v8
	v_lshlrev_b64 v[8:9], 12, v[8:9]
	v_lshl_add_u64 v[8:9], v[2:3], 0, v[8:9]
	s_waitcnt lgkmcnt(0)
	flat_store_dwordx4 v[8:9], v[4:7] nt
	s_nop 1
	v_add_u32_e32 v4, 0x1e00, v132
	v_ashrrev_i32_e32 v8, 5, v4
	v_mad_u64_u32 v[4:5], s[0:1], v8, s72, v[0:1]
	ds_read_b128 v[4:7], v4
	v_ashrrev_i32_e32 v9, 31, v8
	v_lshlrev_b64 v[8:9], 12, v[8:9]
	v_lshl_add_u64 v[2:3], v[2:3], 0, v[8:9]
	s_waitcnt lgkmcnt(0)
	flat_store_dwordx4 v[2:3], v[4:7] nt
	s_waitcnt lgkmcnt(0)
	s_barrier

.LBB0_329:
	v_mov_b32_e32 v134, v204
	s_waitcnt vmcnt(0)
	v_and_b32_e32 v0, 15, v134
	v_ashrrev_i32_e32 v135, 2, v134
	v_and_b32_e32 v136, 0xffffffc0, v135
	v_or_b32_e32 v135, s10, v0
	v_add_u32_e32 v138, v135, v136
	v_ashrrev_i32_e32 v139, 31, v138
	v_lshl_add_u64 v[138:139], v[138:139], 3, v[130:131]
	s_barrier
	flat_load_dwordx2 v[138:139], v[138:139]
	v_mov_b32_e32 v140, 0x358637bd
	s_mov_b64 s[0:1], 0x1e364800
	v_mov_b32_e32 v253, 0x358637bd
	s_waitcnt vmcnt(0) lgkmcnt(0)
	v_ffbh_u32_e32 v137, v139
	v_min_u32_e32 v137, 32, v137
	v_lshlrev_b64 v[138:139], v137, v[138:139]
	v_min_u32_e32 v138, 1, v138
	v_or_b32_e32 v138, v139, v138
	v_cvt_f32_u32_e32 v138, v138
	v_sub_u32_e32 v137, 32, v137
	v_ldexp_f32 v137, v138, v137
	v_fmamk_f32 v137, v137, 0x30000000, v140
	v_cmp_gt_f32_e32 vcc, s33, v137
	v_mul_f32_e32 v138, 0x4b800000, v137
	s_nop 0
	v_cndmask_b32_e32 v137, v137, v138, vcc
	v_rsq_f32_e32 v137, v137
	s_nop 0
	v_mul_f32_e32 v138, 0x45800000, v137
	v_cndmask_b32_e32 v137, v137, v138, vcc
	v_mul_f32_e32 v137, 0x3e38aa3b, v137
	v_mul_f32_e32 v126, v126, v137
	v_mul_f32_e32 v127, v127, v137
	v_or_b32_e32 v138, v136, v0
	v_mul_f32_e32 v139, v128, v137
	v_cvt_pk_bf16_f32 v128, v126, v127
	v_lshrrev_b32_e32 v126, 1, v134
	v_mul_lo_u32 v138, v138, s72
	v_mul_f32_e32 v129, v129, v137
	v_and_b32_e32 v126, 24, v126
	v_and_b32_e32 v127, 0xc0, v134
	v_mul_f32_e32 v114, v114, v137
	v_mul_f32_e32 v115, v115, v137
	v_mul_f32_e32 v116, v116, v137
	v_mul_f32_e32 v117, v117, v137
	v_cvt_pk_bf16_f32 v129, v139, v129
	v_add3_u32 v138, v138, v127, v126
	v_cvt_pk_bf16_f32 v114, v114, v115
	v_cvt_pk_bf16_f32 v115, v116, v117
	ds_write2_b64 v138, v[128:129], v[114:115] offset1:4
	v_mul_f32_e32 v114, v122, v137
	v_mul_f32_e32 v115, v123, v137
	v_mul_f32_e32 v116, v124, v137
	v_mul_f32_e32 v117, v125, v137
	v_cvt_pk_bf16_f32 v114, v114, v115
	v_cvt_pk_bf16_f32 v115, v116, v117
	v_mul_f32_e32 v116, v118, v137
	v_mul_f32_e32 v117, v119, v137
	v_mul_f32_e32 v118, v120, v137
	v_mul_f32_e32 v119, v121, v137
	v_cvt_pk_bf16_f32 v116, v116, v117
	v_cvt_pk_bf16_f32 v117, v118, v119
	ds_write2_b64 v138, v[114:115], v[116:117] offset0:32 offset1:36
	v_or_b32_e32 v116, 16, v136
	v_add_u32_e32 v114, v116, v135
	v_ashrrev_i32_e32 v115, 31, v114
	v_lshl_add_u64 v[114:115], v[114:115], 3, v[130:131]
	flat_load_dwordx2 v[114:115], v[114:115]
	s_waitcnt vmcnt(0) lgkmcnt(0)
	v_ffbh_u32_e32 v117, v115
	v_min_u32_e32 v117, 32, v117
	v_lshlrev_b64 v[114:115], v117, v[114:115]
	v_min_u32_e32 v114, 1, v114
	v_or_b32_e32 v114, v115, v114
	v_cvt_f32_u32_e32 v114, v114
	v_sub_u32_e32 v115, 32, v117
	v_ldexp_f32 v114, v114, v115
	v_fmamk_f32 v114, v114, 0x30000000, v140
	v_cmp_gt_f32_e32 vcc, s33, v114
	v_mul_f32_e32 v115, 0x4b800000, v114
	s_nop 0
	v_cndmask_b32_e32 v114, v114, v115, vcc
	v_rsq_f32_e32 v114, v114
	s_nop 0
	v_mul_f32_e32 v115, 0x45800000, v114
	v_cndmask_b32_e32 v114, v114, v115, vcc
	v_mul_f32_e32 v114, 0x3e38aa3b, v114
	v_or_b32_e32 v115, v116, v0
	v_mul_lo_u32 v115, v115, s72
	v_mul_f32_e32 v102, v102, v114
	v_mul_f32_e32 v103, v103, v114
	v_mul_f32_e32 v104, v104, v114
	v_mul_f32_e32 v105, v105, v114
	v_mul_f32_e32 v98, v98, v114
	v_mul_f32_e32 v99, v99, v114
	v_mul_f32_e32 v100, v100, v114
	v_mul_f32_e32 v101, v101, v114
	v_cvt_pk_bf16_f32 v102, v102, v103
	v_cvt_pk_bf16_f32 v103, v104, v105
	v_add3_u32 v104, v115, v127, v126
	v_cvt_pk_bf16_f32 v98, v98, v99
	v_cvt_pk_bf16_f32 v99, v100, v101
	ds_write2_b64 v104, v[102:103], v[98:99] offset1:4
	v_mul_f32_e32 v98, v110, v114
	v_mul_f32_e32 v99, v111, v114
	v_mul_f32_e32 v100, v112, v114
	v_mul_f32_e32 v101, v113, v114
	v_cvt_pk_bf16_f32 v98, v98, v99
	v_cvt_pk_bf16_f32 v99, v100, v101
	v_mul_f32_e32 v100, v106, v114
	v_mul_f32_e32 v101, v107, v114
	v_mul_f32_e32 v102, v108, v114
	v_mul_f32_e32 v103, v109, v114
	v_cvt_pk_bf16_f32 v100, v100, v101
	v_cvt_pk_bf16_f32 v101, v102, v103
	ds_write2_b64 v104, v[98:99], v[100:101] offset0:32 offset1:36
	v_or_b32_e32 v100, 32, v136
	v_add_u32_e32 v98, v100, v135
	v_ashrrev_i32_e32 v99, 31, v98
	v_lshl_add_u64 v[98:99], v[98:99], 3, v[130:131]
	flat_load_dwordx2 v[98:99], v[98:99]
	s_waitcnt vmcnt(0) lgkmcnt(0)
	v_ffbh_u32_e32 v101, v99
	v_min_u32_e32 v101, 32, v101
	v_lshlrev_b64 v[98:99], v101, v[98:99]
	v_min_u32_e32 v98, 1, v98
	v_or_b32_e32 v98, v99, v98
	v_cvt_f32_u32_e32 v98, v98
	v_sub_u32_e32 v99, 32, v101
	v_ldexp_f32 v98, v98, v99
	v_fmamk_f32 v98, v98, 0x30000000, v140
	v_cmp_gt_f32_e32 vcc, s33, v98
	v_mul_f32_e32 v99, 0x4b800000, v98
	s_nop 0
	v_cndmask_b32_e32 v98, v98, v99, vcc
	v_rsq_f32_e32 v98, v98
	s_nop 0
	v_mul_f32_e32 v99, 0x45800000, v98
	v_cndmask_b32_e32 v98, v98, v99, vcc
	v_mul_f32_e32 v98, 0x3e38aa3b, v98
	v_or_b32_e32 v99, v100, v0
	v_mul_lo_u32 v99, v99, s72
	v_mul_f32_e32 v86, v86, v98
	v_mul_f32_e32 v87, v87, v98
	v_mul_f32_e32 v88, v88, v98
	v_mul_f32_e32 v89, v89, v98
	v_mul_f32_e32 v82, v82, v98
	v_mul_f32_e32 v83, v83, v98
	v_mul_f32_e32 v84, v84, v98
	v_mul_f32_e32 v85, v85, v98
	v_cvt_pk_bf16_f32 v86, v86, v87
	v_cvt_pk_bf16_f32 v87, v88, v89
	v_add3_u32 v88, v99, v127, v126
	v_cvt_pk_bf16_f32 v82, v82, v83
	v_cvt_pk_bf16_f32 v83, v84, v85
	ds_write2_b64 v88, v[86:87], v[82:83] offset1:4
	v_mul_f32_e32 v82, v94, v98
	v_mul_f32_e32 v83, v95, v98
	v_mul_f32_e32 v84, v96, v98
	v_mul_f32_e32 v85, v97, v98
	v_cvt_pk_bf16_f32 v82, v82, v83
	v_cvt_pk_bf16_f32 v83, v84, v85
	v_mul_f32_e32 v84, v90, v98
	v_mul_f32_e32 v85, v91, v98
	v_mul_f32_e32 v86, v92, v98
	v_mul_f32_e32 v87, v93, v98
	v_cvt_pk_bf16_f32 v84, v84, v85
	v_cvt_pk_bf16_f32 v85, v86, v87
	ds_write2_b64 v88, v[82:83], v[84:85] offset0:32 offset1:36
	v_or_b32_e32 v84, 48, v136
	v_add_u32_e32 v82, v84, v135
	v_ashrrev_i32_e32 v83, 31, v82
	v_lshl_add_u64 v[82:83], v[82:83], 3, v[130:131]
	flat_load_dwordx2 v[82:83], v[82:83]
	s_waitcnt vmcnt(0) lgkmcnt(0)
	v_ffbh_u32_e32 v85, v83
	v_min_u32_e32 v85, 32, v85
	v_lshlrev_b64 v[82:83], v85, v[82:83]
	v_min_u32_e32 v82, 1, v82
	v_or_b32_e32 v82, v83, v82
	v_cvt_f32_u32_e32 v82, v82
	v_sub_u32_e32 v83, 32, v85
	v_ldexp_f32 v82, v82, v83
	v_fmamk_f32 v82, v82, 0x30000000, v140
	v_cmp_gt_f32_e32 vcc, s33, v82
	v_mul_f32_e32 v83, 0x4b800000, v82
	s_nop 0
	v_cndmask_b32_e32 v82, v82, v83, vcc
	v_rsq_f32_e32 v82, v82
	s_nop 0
	v_mul_f32_e32 v83, 0x45800000, v82
	v_cndmask_b32_e32 v82, v82, v83, vcc
	v_mul_f32_e32 v82, 0x3e38aa3b, v82
	v_or_b32_e32 v83, v84, v0
	v_mul_lo_u32 v83, v83, s72
	v_mul_f32_e32 v70, v70, v82
	v_mul_f32_e32 v71, v71, v82
	v_mul_f32_e32 v72, v72, v82
	v_mul_f32_e32 v73, v73, v82
	v_mul_f32_e32 v66, v66, v82
	v_mul_f32_e32 v67, v67, v82
	v_mul_f32_e32 v68, v68, v82
	v_mul_f32_e32 v69, v69, v82
	v_cvt_pk_bf16_f32 v70, v70, v71
	v_cvt_pk_bf16_f32 v71, v72, v73
	v_add3_u32 v72, v83, v127, v126
	v_cvt_pk_bf16_f32 v66, v66, v67
	v_cvt_pk_bf16_f32 v67, v68, v69
	ds_write2_b64 v72, v[70:71], v[66:67] offset1:4
	v_mul_f32_e32 v66, v78, v82
	v_mul_f32_e32 v67, v79, v82
	v_mul_f32_e32 v68, v80, v82
	v_mul_f32_e32 v69, v81, v82
	v_cvt_pk_bf16_f32 v66, v66, v67
	v_cvt_pk_bf16_f32 v67, v68, v69
	v_mul_f32_e32 v68, v74, v82
	v_mul_f32_e32 v69, v75, v82
	v_mul_f32_e32 v70, v76, v82
	v_mul_f32_e32 v71, v77, v82
	v_cvt_pk_bf16_f32 v68, v68, v69
	v_cvt_pk_bf16_f32 v69, v70, v71
	ds_write2_b64 v72, v[66:67], v[68:69] offset0:32 offset1:36
	v_add_u32_e32 v68, 0x80, v136
	v_add_u32_e32 v66, v68, v135
	v_ashrrev_i32_e32 v67, 31, v66
	v_lshl_add_u64 v[66:67], v[66:67], 3, v[130:131]
	flat_load_dwordx2 v[66:67], v[66:67]
	s_waitcnt vmcnt(0) lgkmcnt(0)
	v_ffbh_u32_e32 v69, v67
	v_min_u32_e32 v69, 32, v69
	v_lshlrev_b64 v[66:67], v69, v[66:67]
	v_min_u32_e32 v66, 1, v66
	v_or_b32_e32 v66, v67, v66
	v_cvt_f32_u32_e32 v66, v66
	v_sub_u32_e32 v67, 32, v69
	v_ldexp_f32 v66, v66, v67
	v_fmamk_f32 v66, v66, 0x30000000, v140
	v_cmp_gt_f32_e32 vcc, s33, v66
	v_mul_f32_e32 v67, 0x4b800000, v66
	s_nop 0
	v_cndmask_b32_e32 v66, v66, v67, vcc
	v_rsq_f32_e32 v66, v66
	s_nop 0
	v_mul_f32_e32 v67, 0x45800000, v66
	v_cndmask_b32_e32 v66, v66, v67, vcc
	v_mul_f32_e32 v66, 0x3e38aa3b, v66
	v_or_b32_e32 v67, v68, v0
	v_mul_lo_u32 v67, v67, s72
	v_mul_f32_e32 v54, v54, v66
	v_mul_f32_e32 v55, v55, v66
	v_mul_f32_e32 v56, v56, v66
	v_mul_f32_e32 v57, v57, v66
	v_mul_f32_e32 v50, v50, v66
	v_mul_f32_e32 v51, v51, v66
	v_mul_f32_e32 v52, v52, v66
	v_mul_f32_e32 v53, v53, v66
	v_cvt_pk_bf16_f32 v54, v54, v55
	v_cvt_pk_bf16_f32 v55, v56, v57
	v_add3_u32 v56, v67, v127, v126
	v_cvt_pk_bf16_f32 v50, v50, v51
	v_cvt_pk_bf16_f32 v51, v52, v53
	ds_write2_b64 v56, v[54:55], v[50:51] offset1:4
	v_mul_f32_e32 v50, v62, v66
	v_mul_f32_e32 v51, v63, v66
	v_mul_f32_e32 v52, v64, v66
	v_mul_f32_e32 v53, v65, v66
	v_cvt_pk_bf16_f32 v50, v50, v51
	v_cvt_pk_bf16_f32 v51, v52, v53
	v_mul_f32_e32 v52, v58, v66
	v_mul_f32_e32 v53, v59, v66
	v_mul_f32_e32 v54, v60, v66
	v_mul_f32_e32 v55, v61, v66
	v_cvt_pk_bf16_f32 v52, v52, v53
	v_cvt_pk_bf16_f32 v53, v54, v55
	ds_write2_b64 v56, v[50:51], v[52:53] offset0:32 offset1:36
	v_add_u32_e32 v52, 0x90, v136
	v_add_u32_e32 v50, v52, v135
	v_ashrrev_i32_e32 v51, 31, v50
	v_lshl_add_u64 v[50:51], v[50:51], 3, v[130:131]
	flat_load_dwordx2 v[50:51], v[50:51]
	s_waitcnt vmcnt(0) lgkmcnt(0)
	v_ffbh_u32_e32 v53, v51
	v_min_u32_e32 v53, 32, v53
	v_lshlrev_b64 v[50:51], v53, v[50:51]
	v_min_u32_e32 v50, 1, v50
	v_or_b32_e32 v50, v51, v50
	v_cvt_f32_u32_e32 v50, v50
	v_sub_u32_e32 v51, 32, v53
	v_ldexp_f32 v50, v50, v51
	v_fmamk_f32 v50, v50, 0x30000000, v140
	v_cmp_gt_f32_e32 vcc, s33, v50
	v_mul_f32_e32 v51, 0x4b800000, v50
	s_nop 0
	v_cndmask_b32_e32 v50, v50, v51, vcc
	v_rsq_f32_e32 v50, v50
	s_nop 0
	v_mul_f32_e32 v51, 0x45800000, v50
	v_cndmask_b32_e32 v50, v50, v51, vcc
	v_mul_f32_e32 v50, 0x3e38aa3b, v50
	v_or_b32_e32 v51, v52, v0
	v_mul_lo_u32 v51, v51, s72
	v_mul_f32_e32 v38, v38, v50
	v_mul_f32_e32 v39, v39, v50
	v_mul_f32_e32 v40, v40, v50
	v_mul_f32_e32 v41, v41, v50
	v_mul_f32_e32 v34, v34, v50
	v_mul_f32_e32 v35, v35, v50
	v_mul_f32_e32 v36, v36, v50
	v_mul_f32_e32 v37, v37, v50
	v_cvt_pk_bf16_f32 v38, v38, v39
	v_cvt_pk_bf16_f32 v39, v40, v41
	v_add3_u32 v40, v51, v127, v126
	v_cvt_pk_bf16_f32 v34, v34, v35
	v_cvt_pk_bf16_f32 v35, v36, v37
	ds_write2_b64 v40, v[38:39], v[34:35] offset1:4
	v_mul_f32_e32 v34, v46, v50
	v_mul_f32_e32 v35, v47, v50
	v_mul_f32_e32 v36, v48, v50
	v_mul_f32_e32 v37, v49, v50
	v_cvt_pk_bf16_f32 v34, v34, v35
	v_cvt_pk_bf16_f32 v35, v36, v37
	v_mul_f32_e32 v36, v42, v50
	v_mul_f32_e32 v37, v43, v50
	v_mul_f32_e32 v38, v44, v50
	v_mul_f32_e32 v39, v45, v50
	v_cvt_pk_bf16_f32 v36, v36, v37
	v_cvt_pk_bf16_f32 v37, v38, v39
	ds_write2_b64 v40, v[34:35], v[36:37] offset0:32 offset1:36
	v_add_u32_e32 v36, 0xa0, v136
	v_add_u32_e32 v34, v36, v135
	v_ashrrev_i32_e32 v35, 31, v34
	v_lshl_add_u64 v[34:35], v[34:35], 3, v[130:131]
	flat_load_dwordx2 v[34:35], v[34:35]
	s_waitcnt vmcnt(0) lgkmcnt(0)
	v_ffbh_u32_e32 v37, v35
	v_min_u32_e32 v37, 32, v37
	v_lshlrev_b64 v[34:35], v37, v[34:35]
	v_min_u32_e32 v34, 1, v34
	v_or_b32_e32 v34, v35, v34
	v_cvt_f32_u32_e32 v34, v34
	v_sub_u32_e32 v35, 32, v37
	v_ldexp_f32 v34, v34, v35
	v_fmamk_f32 v34, v34, 0x30000000, v140
	v_cmp_gt_f32_e32 vcc, s33, v34
	v_mul_f32_e32 v35, 0x4b800000, v34
	s_nop 0
	v_cndmask_b32_e32 v34, v34, v35, vcc
	v_rsq_f32_e32 v34, v34
	s_nop 0
	v_mul_f32_e32 v35, 0x45800000, v34
	v_cndmask_b32_e32 v34, v34, v35, vcc
	v_mul_f32_e32 v34, 0x3e38aa3b, v34
	v_or_b32_e32 v35, v36, v0
	v_mul_lo_u32 v35, v35, s72
	v_mul_f32_e32 v22, v22, v34
	v_mul_f32_e32 v23, v23, v34
	v_mul_f32_e32 v24, v24, v34
	v_mul_f32_e32 v25, v25, v34
	v_mul_f32_e32 v18, v18, v34
	v_mul_f32_e32 v19, v19, v34
	v_mul_f32_e32 v20, v20, v34
	v_mul_f32_e32 v21, v21, v34
	v_cvt_pk_bf16_f32 v22, v22, v23
	v_cvt_pk_bf16_f32 v23, v24, v25
	v_add3_u32 v24, v35, v127, v126
	v_cvt_pk_bf16_f32 v18, v18, v19
	v_cvt_pk_bf16_f32 v19, v20, v21
	ds_write2_b64 v24, v[22:23], v[18:19] offset1:4
	v_mul_f32_e32 v18, v30, v34
	v_mul_f32_e32 v19, v31, v34
	v_mul_f32_e32 v20, v32, v34
	v_mul_f32_e32 v21, v33, v34
	v_cvt_pk_bf16_f32 v18, v18, v19
	v_cvt_pk_bf16_f32 v19, v20, v21
	v_mul_f32_e32 v20, v26, v34
	v_mul_f32_e32 v21, v27, v34
	v_mul_f32_e32 v22, v28, v34
	v_mul_f32_e32 v23, v29, v34
	v_cvt_pk_bf16_f32 v20, v20, v21
	v_cvt_pk_bf16_f32 v21, v22, v23
	ds_write2_b64 v24, v[18:19], v[20:21] offset0:32 offset1:36
	v_add_u32_e32 v20, 0xb0, v136
	v_add_u32_e32 v18, v20, v135
	v_ashrrev_i32_e32 v19, 31, v18
	v_lshl_add_u64 v[18:19], v[18:19], 3, v[130:131]
	flat_load_dwordx2 v[18:19], v[18:19]
	v_or_b32_e32 v0, v20, v0
	v_mul_lo_u32 v0, v0, s72
	v_add3_u32 v0, v0, v127, v126
	s_waitcnt vmcnt(0) lgkmcnt(0)
	v_ffbh_u32_e32 v21, v19
	v_min_u32_e32 v21, 32, v21
	v_lshlrev_b64 v[18:19], v21, v[18:19]
	v_min_u32_e32 v18, 1, v18
	v_or_b32_e32 v18, v19, v18
	v_cvt_f32_u32_e32 v18, v18
	v_sub_u32_e32 v19, 32, v21
	v_ldexp_f32 v18, v18, v19
	v_fmamk_f32 v18, v18, 0x30000000, v140
	v_cmp_gt_f32_e32 vcc, s33, v18
	v_mul_f32_e32 v19, 0x4b800000, v18
	s_nop 0
	v_cndmask_b32_e32 v18, v18, v19, vcc
	v_rsq_f32_e32 v18, v18
	s_nop 0
	v_mul_f32_e32 v19, 0x45800000, v18
	v_cndmask_b32_e32 v18, v18, v19, vcc
	v_mul_f32_e32 v18, 0x3e38aa3b, v18
	v_mul_f32_e32 v6, v6, v18
	v_mul_f32_e32 v7, v7, v18
	v_mul_f32_e32 v8, v8, v18
	v_mul_f32_e32 v9, v9, v18
	v_mul_f32_e32 v2, v2, v18
	v_mul_f32_e32 v3, v3, v18
	v_mul_f32_e32 v4, v4, v18
	v_mul_f32_e32 v5, v5, v18
	v_cvt_pk_bf16_f32 v6, v6, v7
	v_cvt_pk_bf16_f32 v7, v8, v9
	v_cvt_pk_bf16_f32 v2, v2, v3
	v_cvt_pk_bf16_f32 v3, v4, v5
	ds_write2_b64 v0, v[6:7], v[2:3] offset1:4
	v_mul_f32_e32 v2, v14, v18
	v_mul_f32_e32 v3, v15, v18
	v_mul_f32_e32 v4, v16, v18
	v_mul_f32_e32 v5, v17, v18
	v_cvt_pk_bf16_f32 v2, v2, v3
	v_cvt_pk_bf16_f32 v3, v4, v5
	v_mul_f32_e32 v4, v10, v18
	v_mul_f32_e32 v5, v11, v18
	v_mul_f32_e32 v6, v12, v18
	v_mul_f32_e32 v7, v13, v18
	v_cvt_pk_bf16_f32 v4, v4, v5
	v_cvt_pk_bf16_f32 v5, v6, v7
	ds_write2_b64 v0, v[2:3], v[4:5] offset0:32 offset1:36
	v_lshlrev_b32_e32 v0, 4, v134
	v_lshl_add_u64 v[2:3], s[8:9], 1, v[132:133]
	v_and_b32_e32 v0, 0x1f0, v0
	v_lshl_add_u64 v[2:3], v[2:3], 0, v[0:1]
	v_ashrrev_i32_e32 v8, 5, v134
	v_lshl_add_u64 v[2:3], v[2:3], 0, s[0:1]
	v_mad_u64_u32 v[4:5], s[0:1], v8, s72, v[0:1]
	s_waitcnt lgkmcnt(0)
	s_barrier
	ds_read_b128 v[4:7], v4
	v_ashrrev_i32_e32 v9, 31, v8
	v_lshlrev_b64 v[8:9], 12, v[8:9]
	v_lshl_add_u64 v[8:9], v[2:3], 0, v[8:9]
	s_waitcnt lgkmcnt(0)
	flat_store_dwordx4 v[8:9], v[4:7] nt
	s_nop 1
	v_add_u32_e32 v4, 0x200, v134
	v_ashrrev_i32_e32 v8, 5, v4
	v_mad_u64_u32 v[4:5], s[0:1], v8, s72, v[0:1]
	ds_read_b128 v[4:7], v4
	v_ashrrev_i32_e32 v9, 31, v8
	v_lshlrev_b64 v[8:9], 12, v[8:9]
	v_lshl_add_u64 v[8:9], v[2:3], 0, v[8:9]
	s_waitcnt lgkmcnt(0)
	flat_store_dwordx4 v[8:9], v[4:7] nt
	s_nop 1
	v_add_u32_e32 v4, 0x400, v134
	v_ashrrev_i32_e32 v8, 5, v4
	v_mad_u64_u32 v[4:5], s[0:1], v8, s72, v[0:1]
	ds_read_b128 v[4:7], v4
	v_ashrrev_i32_e32 v9, 31, v8
	v_lshlrev_b64 v[8:9], 12, v[8:9]
	v_lshl_add_u64 v[8:9], v[2:3], 0, v[8:9]
	s_waitcnt lgkmcnt(0)
	flat_store_dwordx4 v[8:9], v[4:7] nt
	s_nop 1
	v_add_u32_e32 v4, 0x600, v134
	v_ashrrev_i32_e32 v8, 5, v4
	v_mad_u64_u32 v[4:5], s[0:1], v8, s72, v[0:1]
	ds_read_b128 v[4:7], v4
	v_ashrrev_i32_e32 v9, 31, v8
	v_lshlrev_b64 v[8:9], 12, v[8:9]
	v_lshl_add_u64 v[8:9], v[2:3], 0, v[8:9]
	s_waitcnt lgkmcnt(0)
	flat_store_dwordx4 v[8:9], v[4:7] nt
	s_nop 1
	v_add_u32_e32 v4, 0x800, v134
	v_ashrrev_i32_e32 v8, 5, v4
	v_mad_u64_u32 v[4:5], s[0:1], v8, s72, v[0:1]
	ds_read_b128 v[4:7], v4
	v_ashrrev_i32_e32 v9, 31, v8
	v_lshlrev_b64 v[8:9], 12, v[8:9]
	v_lshl_add_u64 v[8:9], v[2:3], 0, v[8:9]
	s_waitcnt lgkmcnt(0)
	flat_store_dwordx4 v[8:9], v[4:7] nt
	s_nop 1
	v_add_u32_e32 v4, 0xa00, v134
	v_ashrrev_i32_e32 v8, 5, v4
	v_mad_u64_u32 v[4:5], s[0:1], v8, s72, v[0:1]
	ds_read_b128 v[4:7], v4
	v_ashrrev_i32_e32 v9, 31, v8
	v_lshlrev_b64 v[8:9], 12, v[8:9]
	v_lshl_add_u64 v[8:9], v[2:3], 0, v[8:9]
	s_waitcnt lgkmcnt(0)
	flat_store_dwordx4 v[8:9], v[4:7] nt
	s_nop 1
	v_add_u32_e32 v4, 0xc00, v134
	v_ashrrev_i32_e32 v8, 5, v4
	v_mad_u64_u32 v[4:5], s[0:1], v8, s72, v[0:1]
	ds_read_b128 v[4:7], v4
	v_ashrrev_i32_e32 v9, 31, v8
	v_lshlrev_b64 v[8:9], 12, v[8:9]
	v_lshl_add_u64 v[8:9], v[2:3], 0, v[8:9]
	s_waitcnt lgkmcnt(0)
	flat_store_dwordx4 v[8:9], v[4:7] nt
	s_nop 1
	v_add_u32_e32 v4, 0xe00, v134
	v_ashrrev_i32_e32 v8, 5, v4
	v_mad_u64_u32 v[4:5], s[0:1], v8, s72, v[0:1]
	ds_read_b128 v[4:7], v4
	v_ashrrev_i32_e32 v9, 31, v8
	v_lshlrev_b64 v[8:9], 12, v[8:9]
	v_lshl_add_u64 v[8:9], v[2:3], 0, v[8:9]
	s_waitcnt lgkmcnt(0)
	flat_store_dwordx4 v[8:9], v[4:7] nt
	s_nop 1
	v_add_u32_e32 v4, 0x1000, v134
	v_ashrrev_i32_e32 v8, 5, v4
	v_mad_u64_u32 v[4:5], s[0:1], v8, s72, v[0:1]
	ds_read_b128 v[4:7], v4
	v_ashrrev_i32_e32 v9, 31, v8
	v_lshlrev_b64 v[8:9], 12, v[8:9]
	v_lshl_add_u64 v[8:9], v[2:3], 0, v[8:9]
	s_waitcnt lgkmcnt(0)
	flat_store_dwordx4 v[8:9], v[4:7] nt
	s_nop 1
	v_add_u32_e32 v4, 0x1200, v134
	v_ashrrev_i32_e32 v8, 5, v4
	v_mad_u64_u32 v[4:5], s[0:1], v8, s72, v[0:1]
	ds_read_b128 v[4:7], v4
	v_ashrrev_i32_e32 v9, 31, v8
	v_lshlrev_b64 v[8:9], 12, v[8:9]
	v_lshl_add_u64 v[8:9], v[2:3], 0, v[8:9]
	s_waitcnt lgkmcnt(0)
	flat_store_dwordx4 v[8:9], v[4:7] nt
	s_nop 1
	v_add_u32_e32 v4, 0x1400, v134
	v_ashrrev_i32_e32 v8, 5, v4
	v_mad_u64_u32 v[4:5], s[0:1], v8, s72, v[0:1]
	ds_read_b128 v[4:7], v4
	v_ashrrev_i32_e32 v9, 31, v8
	v_lshlrev_b64 v[8:9], 12, v[8:9]
	v_lshl_add_u64 v[8:9], v[2:3], 0, v[8:9]
	s_waitcnt lgkmcnt(0)
	flat_store_dwordx4 v[8:9], v[4:7] nt
	s_nop 1
	v_add_u32_e32 v4, 0x1600, v134
	v_ashrrev_i32_e32 v8, 5, v4
	v_mad_u64_u32 v[4:5], s[0:1], v8, s72, v[0:1]
	ds_read_b128 v[4:7], v4
	v_ashrrev_i32_e32 v9, 31, v8
	v_lshlrev_b64 v[8:9], 12, v[8:9]
	v_lshl_add_u64 v[8:9], v[2:3], 0, v[8:9]
	s_waitcnt lgkmcnt(0)
	flat_store_dwordx4 v[8:9], v[4:7] nt
	s_nop 1
	v_add_u32_e32 v4, 0x1800, v134
	v_ashrrev_i32_e32 v8, 5, v4
	v_mad_u64_u32 v[4:5], s[0:1], v8, s72, v[0:1]
	ds_read_b128 v[4:7], v4
	v_ashrrev_i32_e32 v9, 31, v8
	v_lshlrev_b64 v[8:9], 12, v[8:9]
	v_lshl_add_u64 v[8:9], v[2:3], 0, v[8:9]
	s_waitcnt lgkmcnt(0)
	flat_store_dwordx4 v[8:9], v[4:7] nt
	s_nop 1
	v_add_u32_e32 v4, 0x1a00, v134
	v_ashrrev_i32_e32 v8, 5, v4
	v_mad_u64_u32 v[4:5], s[0:1], v8, s72, v[0:1]
	ds_read_b128 v[4:7], v4
	v_ashrrev_i32_e32 v9, 31, v8
	v_lshlrev_b64 v[8:9], 12, v[8:9]
	v_lshl_add_u64 v[8:9], v[2:3], 0, v[8:9]
	s_waitcnt lgkmcnt(0)
	flat_store_dwordx4 v[8:9], v[4:7] nt
	s_nop 1
	v_add_u32_e32 v4, 0x1c00, v134
	v_ashrrev_i32_e32 v8, 5, v4
	v_mad_u64_u32 v[4:5], s[0:1], v8, s72, v[0:1]
	ds_read_b128 v[4:7], v4
	v_ashrrev_i32_e32 v9, 31, v8
	v_lshlrev_b64 v[8:9], 12, v[8:9]
	v_lshl_add_u64 v[8:9], v[2:3], 0, v[8:9]
	s_waitcnt lgkmcnt(0)
	flat_store_dwordx4 v[8:9], v[4:7] nt
	s_nop 1
	v_add_u32_e32 v4, 0x1e00, v134
	v_ashrrev_i32_e32 v8, 5, v4
	v_mad_u64_u32 v[4:5], s[0:1], v8, s72, v[0:1]
	ds_read_b128 v[4:7], v4
	v_ashrrev_i32_e32 v9, 31, v8
	v_lshlrev_b64 v[8:9], 12, v[8:9]
	v_lshl_add_u64 v[2:3], v[2:3], 0, v[8:9]
	s_waitcnt lgkmcnt(0)
	flat_store_dwordx4 v[2:3], v[4:7] nt
	s_waitcnt lgkmcnt(0)
	s_barrier
